# stack E + all s_setprio removed in the NSA attention phase (arbitration experiment)
# baseline (speedup 1.0000x reference)
.LBB0_985:
	s_waitcnt lgkmcnt(0)
	s_barrier
	s_waitcnt vmcnt(0)
	v_mov_b64_e32 v[16:17], v[32:33]
	s_nop 2
	v_mov_b64_e32 v[82:83], v[118:119]
	v_mov_b64_e32 v[18:19], v[34:35]
	v_mov_b64_e32 v[20:21], v[36:37]
	v_mov_b64_e32 v[22:23], v[38:39]
	v_mov_b64_e32 v[24:25], v[40:41]
	v_mov_b64_e32 v[26:27], v[42:43]
	v_mov_b64_e32 v[28:29], v[44:45]
	v_mov_b64_e32 v[30:31], v[46:47]
	v_mov_b64_e32 v[84:85], v[120:121]

.LBB0_1010:
	s_add_i32 s0, s23, 0xffffff40
	s_and_b32 s0, s0, 0x80
	s_mulk_i32 s0, 0xa0
	s_waitcnt lgkmcnt(6)
	v_add_u32_e32 v92, s0, v153
	ds_read_b128 v[16:19], v92
	ds_read_b128 v[20:23], v92 offset:64
	ds_read_b128 v[24:27], v92 offset:2560
	ds_read_b128 v[28:31], v92 offset:2624
	ds_read_b128 v[32:35], v92 offset:5120
	ds_read_b128 v[36:39], v92 offset:5184
	ds_read_b128 v[40:43], v92 offset:7680
	s_waitcnt lgkmcnt(12)
	ds_read_b128 v[94:97], v92 offset:7744
	s_waitcnt lgkmcnt(7)
	v_mfma_f32_16x16x32_bf16 v[16:19], v[16:19], v[60:63], 0
	s_waitcnt lgkmcnt(6)
	v_mfma_f32_16x16x32_bf16 v[106:109], v[20:23], v[56:59], v[16:19]
	s_waitcnt lgkmcnt(5)
	v_mfma_f32_16x16x32_bf16 v[16:19], v[24:27], v[60:63], 0
	s_waitcnt lgkmcnt(4)
	v_mfma_f32_16x16x32_bf16 v[24:27], v[28:31], v[56:59], v[16:19]
	s_waitcnt lgkmcnt(3)
	v_mfma_f32_16x16x32_bf16 v[16:19], v[32:35], v[60:63], 0
	s_waitcnt lgkmcnt(2)
	v_mfma_f32_16x16x32_bf16 v[20:23], v[36:39], v[56:59], v[16:19]
	s_waitcnt lgkmcnt(1)
	v_mfma_f32_16x16x32_bf16 v[16:19], v[40:43], v[60:63], 0
	s_waitcnt lgkmcnt(0)
	v_mfma_f32_16x16x32_bf16 v[16:19], v[94:97], v[56:59], v[16:19]
	v_add_u32_e32 v101, 0x330, v89
	v_cvt_f32_i32_e32 v28, v101
	s_add_i32 s0, s23, 0xffffff7f
	s_cmp_gt_i32 s0, s22
	s_mov_b64 s[0:1], -1
	v_mul_f32_e32 v29, v146, v28
	v_fma_f32 v28, -v146, v28, v85
	v_fmamk_f32 v105, v106, 0x3e38aa3b, v28
	v_add_f32_e32 v102, v82, v28
	v_add_f32_e32 v103, v83, v28
	v_add_f32_e32 v104, v84, v28
	v_sub_f32_e32 v28, v86, v29
	v_sub_f32_e32 v30, v87, v29
	v_sub_f32_e32 v29, v88, v29
	v_fmac_f32_e32 v102, 0x3e38aa3b, v107
	v_fmac_f32_e32 v103, 0x3e38aa3b, v108
	v_fmac_f32_e32 v104, 0x3e38aa3b, v109
	v_fmamk_f32 v100, v24, 0x3e38aa3b, v28
	v_add_f32_e32 v99, v82, v28
	v_add_f32_e32 v98, v83, v28
	v_add_f32_e32 v97, v84, v28
	v_fmamk_f32 v96, v20, 0x3e38aa3b, v30
	v_add_f32_e32 v95, v82, v30
	v_add_f32_e32 v94, v83, v30
	v_add_f32_e32 v93, v84, v30
	v_fmamk_f32 v91, v16, 0x3e38aa3b, v29
	v_add_f32_e32 v24, v82, v29
	v_add_f32_e32 v20, v83, v29
	v_add_f32_e32 v16, v84, v29
	s_cbranch_scc1 .LBB0_1012
	v_mov_b32_e32 v28, v105
	v_mov_b32_e32 v29, v102
	v_mov_b32_e32 v30, v103
	v_mov_b32_e32 v31, v104
	v_exp_f32_e32 v28, v28
	v_exp_f32_e32 v29, v29
	v_fmamk_f32 v33, v25, 0x3e38aa3b, v99
	v_mov_b32_e32 v32, v100
	v_exp_f32_e32 v30, v30
	v_exp_f32_e32 v31, v31
	v_fmamk_f32 v34, v26, 0x3e38aa3b, v98
	v_fmamk_f32 v35, v27, 0x3e38aa3b, v97
	v_pk_add_f32 v[106:107], v[28:29], 0 op_sel_hi:[1,0]
	v_exp_f32_e32 v32, v32
	v_exp_f32_e32 v33, v33
	v_fmamk_f32 v37, v21, 0x3e38aa3b, v95
	v_mov_b32_e32 v36, v96
	v_pk_add_f32 v[106:107], v[106:107], v[30:31]
	v_exp_f32_e32 v34, v34
	v_exp_f32_e32 v35, v35
	v_fmamk_f32 v38, v22, 0x3e38aa3b, v94
	v_fmamk_f32 v39, v23, 0x3e38aa3b, v93
	v_pk_add_f32 v[106:107], v[106:107], v[32:33]
	v_exp_f32_e32 v36, v36
	v_exp_f32_e32 v37, v37
	v_fmamk_f32 v41, v17, 0x3e38aa3b, v24
	v_mov_b32_e32 v40, v91
	v_pk_add_f32 v[106:107], v[106:107], v[34:35]
	v_exp_f32_e32 v38, v38
	v_exp_f32_e32 v39, v39
	v_fmamk_f32 v42, v18, 0x3e38aa3b, v20
	v_fmamk_f32 v43, v19, 0x3e38aa3b, v16
	v_pk_add_f32 v[106:107], v[106:107], v[36:37]
	v_exp_f32_e32 v40, v40
	v_exp_f32_e32 v41, v41
	v_pk_add_f32 v[106:107], v[106:107], v[38:39]
	v_exp_f32_e32 v42, v42
	v_exp_f32_e32 v43, v43
	s_mov_b64 s[0:1], 0
	v_pk_add_f32 v[106:107], v[106:107], v[40:41]
	s_nop 0
	v_pk_add_f32 v[106:107], v[106:107], v[42:43]
	s_nop 0
	v_add_f32_e32 v90, v106, v107

.LBB0_1014:
	v_mul_f32_e32 v16, 0.5, v31
	ds_bpermute_b32 v16, v181, v16
	v_add_f32_e32 v18, v28, v29
	v_fma_f32 v19, 0.5, v31, v30
	v_add_f32_e32 v18, v18, v19
	v_add_u32_e32 v91, s23, v170
	s_waitcnt lgkmcnt(0)
	v_cndmask_b32_e64 v19, v16, v81, s[4:5]
	v_add_f32_e32 v18, v18, v19
	v_mul_f32_e32 v19, 0.5, v35
	v_add_u32_e32 v17, 0x13f40, v91
	ds_bpermute_b32 v19, v181, v19
	ds_write_b32 v17, v18
	v_add_f32_e32 v17, v32, v33
	v_fma_f32 v18, 0.5, v35, v34
	v_add_f32_e32 v17, v17, v18
	v_mul_f32_e32 v18, 0.5, v39
	ds_bpermute_b32 v18, v181, v18
	s_waitcnt lgkmcnt(2)
	v_cndmask_b32_e64 v16, v19, v16, s[4:5]
	v_add_f32_e32 v16, v17, v16
	v_add_u32_e32 v17, 0x13f50, v91
	ds_write_b32 v17, v16
	v_add_f32_e32 v16, v36, v37
	v_fma_f32 v17, 0.5, v39, v38
	v_add_f32_e32 v16, v16, v17
	s_waitcnt lgkmcnt(1)
	v_cndmask_b32_e64 v17, v18, v19, s[4:5]
	v_mul_f32_e32 v19, 0.5, v43
	ds_bpermute_b32 v81, v181, v19
	v_add_f32_e32 v16, v16, v17
	v_add_u32_e32 v17, 0x13f60, v91
	ds_write_b32 v17, v16
	v_add_f32_e32 v16, v40, v41
	v_fma_f32 v17, 0.5, v43, v42
	v_add_f32_e32 v16, v16, v17
	s_waitcnt lgkmcnt(1)
	v_cndmask_b32_e64 v17, v81, v18, s[4:5]
	v_add_f32_e32 v16, v16, v17
	v_add_u32_e32 v17, 0x13f70, v91
	ds_write_b32 v17, v16
	ds_read_b128 v[16:19], v92 offset:40960
	ds_read_b128 v[20:23], v92 offset:43520
	ds_read_b128 v[24:27], v92 offset:46080
	ds_read_b128 v[94:97], v92 offset:48640
	v_cvt_pk_bf16_f32 v28, v28, v29
	v_cvt_pk_bf16_f32 v29, v30, v31
	v_cvt_pk_bf16_f32 v30, v32, v33
	v_cvt_pk_bf16_f32 v31, v34, v35
	s_waitcnt lgkmcnt(3)
	v_mfma_f32_16x16x32_bf16 v[16:19], v[16:19], v[28:31], v[72:75]
	s_waitcnt lgkmcnt(2)
	v_mfma_f32_16x16x32_bf16 v[20:23], v[20:23], v[28:31], v[76:79]
	s_waitcnt lgkmcnt(1)
	v_mfma_f32_16x16x32_bf16 v[24:27], v[24:27], v[28:31], v[68:71]
	s_waitcnt lgkmcnt(0)
	v_mfma_f32_16x16x32_bf16 v[28:31], v[94:97], v[28:31], v[64:67]
	ds_read_b128 v[32:35], v92 offset:41024
	s_nop 0
	ds_read_b128 v[64:67], v92 offset:43584
	ds_read_b128 v[68:71], v92 offset:46144
	ds_read_b128 v[72:75], v92 offset:48704
	v_cvt_pk_bf16_f32 v36, v36, v37
	v_cvt_pk_bf16_f32 v37, v38, v39
	v_cvt_pk_bf16_f32 v38, v40, v41
	v_cvt_pk_bf16_f32 v39, v42, v43
	s_waitcnt lgkmcnt(3)
	v_mfma_f32_16x16x32_bf16 v[16:19], v[32:35], v[36:39], v[16:19]
	s_waitcnt lgkmcnt(2)
	v_mfma_f32_16x16x32_bf16 v[20:23], v[64:67], v[36:39], v[20:23]
	s_waitcnt lgkmcnt(1)
	v_mfma_f32_16x16x32_bf16 v[24:27], v[68:71], v[36:39], v[24:27]
	s_waitcnt lgkmcnt(0)
	v_mfma_f32_16x16x32_bf16 v[28:31], v[72:75], v[36:39], v[28:31]
	s_add_i32 s0, s23, 0xffffff80
	s_and_b32 s0, s0, 0xc0
	s_mulk_i32 s0, 0xa0
	v_add_u32_e32 v92, s0, v153
	ds_read_b128 v[32:35], v92
	ds_read_b128 v[36:39], v92 offset:64
	ds_read_b128 v[40:43], v92 offset:2560
	ds_read_b128 v[64:67], v92 offset:2624
	ds_read_b128 v[68:71], v92 offset:5120
	ds_read_b128 v[72:75], v92 offset:5184
	ds_read_b128 v[76:79], v92 offset:7680
	ds_read_b128 v[94:97], v92 offset:7744
	s_waitcnt lgkmcnt(7)
	v_mfma_f32_16x16x32_bf16 v[32:35], v[32:35], v[60:63], 0
	s_waitcnt lgkmcnt(6)
	v_mfma_f32_16x16x32_bf16 v[98:101], v[36:39], v[56:59], v[32:35]
	s_waitcnt lgkmcnt(5)
	v_mfma_f32_16x16x32_bf16 v[32:35], v[40:43], v[60:63], 0
	s_waitcnt lgkmcnt(4)
	v_mfma_f32_16x16x32_bf16 v[40:43], v[64:67], v[56:59], v[32:35]
	s_waitcnt lgkmcnt(3)
	v_mfma_f32_16x16x32_bf16 v[32:35], v[68:71], v[60:63], 0
	s_waitcnt lgkmcnt(2)
	v_mfma_f32_16x16x32_bf16 v[36:39], v[72:75], v[56:59], v[32:35]
	s_waitcnt lgkmcnt(1)
	v_mfma_f32_16x16x32_bf16 v[32:35], v[76:79], v[60:63], 0
	s_waitcnt lgkmcnt(0)
	v_mfma_f32_16x16x32_bf16 v[32:35], v[94:97], v[56:59], v[32:35]
	v_add_u32_e32 v102, 0xffffff30, v89
	v_cvt_f32_i32_e32 v64, v102
	s_add_i32 s0, s23, 0xffffffbf
	s_cmp_gt_i32 s0, s22
	s_mov_b64 s[0:1], -1
	v_mul_f32_e32 v65, v146, v64
	v_fma_f32 v64, -v146, v64, v85
	v_fmamk_f32 v106, v98, 0x3e38aa3b, v64
	v_add_f32_e32 v103, v82, v64
	v_add_f32_e32 v104, v83, v64
	v_add_f32_e32 v105, v84, v64
	v_sub_f32_e32 v64, v86, v65
	v_sub_f32_e32 v66, v87, v65
	v_sub_f32_e32 v65, v88, v65
	v_fmac_f32_e32 v103, 0x3e38aa3b, v99
	v_fmac_f32_e32 v104, 0x3e38aa3b, v100
	v_fmac_f32_e32 v105, 0x3e38aa3b, v101
	v_fmamk_f32 v101, v40, 0x3e38aa3b, v64
	v_add_f32_e32 v100, v82, v64
	v_add_f32_e32 v99, v83, v64
	v_add_f32_e32 v98, v84, v64
	v_fmamk_f32 v97, v36, 0x3e38aa3b, v66
	v_add_f32_e32 v96, v82, v66
	v_add_f32_e32 v95, v83, v66
	v_add_f32_e32 v94, v84, v66
	v_fmamk_f32 v93, v32, 0x3e38aa3b, v65
	v_add_f32_e32 v40, v82, v65
	v_add_f32_e32 v36, v83, v65
	v_add_f32_e32 v32, v84, v65
	s_cbranch_scc1 .LBB0_1016
	v_mov_b32_e32 v64, v106
	v_mov_b32_e32 v65, v103
	v_mov_b32_e32 v66, v104
	v_mov_b32_e32 v67, v105
	v_exp_f32_e32 v64, v64
	v_exp_f32_e32 v65, v65
	v_fmamk_f32 v69, v41, 0x3e38aa3b, v100
	v_mov_b32_e32 v68, v101
	v_exp_f32_e32 v66, v66
	v_exp_f32_e32 v67, v67
	v_fmamk_f32 v70, v42, 0x3e38aa3b, v99
	v_fmamk_f32 v71, v43, 0x3e38aa3b, v98
	v_pk_add_f32 v[108:109], v[64:65], 0 op_sel_hi:[1,0]
	v_exp_f32_e32 v68, v68
	v_exp_f32_e32 v69, v69
	v_fmamk_f32 v73, v37, 0x3e38aa3b, v96
	v_mov_b32_e32 v72, v97
	v_pk_add_f32 v[108:109], v[108:109], v[66:67]
	v_exp_f32_e32 v70, v70
	v_exp_f32_e32 v71, v71
	v_fmamk_f32 v74, v38, 0x3e38aa3b, v95
	v_fmamk_f32 v75, v39, 0x3e38aa3b, v94
	v_pk_add_f32 v[108:109], v[108:109], v[68:69]
	v_exp_f32_e32 v72, v72
	v_exp_f32_e32 v73, v73
	v_fmamk_f32 v77, v33, 0x3e38aa3b, v40
	v_mov_b32_e32 v76, v93
	v_pk_add_f32 v[108:109], v[108:109], v[70:71]
	v_exp_f32_e32 v74, v74
	v_exp_f32_e32 v75, v75
	v_fmamk_f32 v78, v34, 0x3e38aa3b, v36
	v_fmamk_f32 v79, v35, 0x3e38aa3b, v32
	v_pk_add_f32 v[108:109], v[108:109], v[72:73]
	v_exp_f32_e32 v76, v76
	v_exp_f32_e32 v77, v77
	v_pk_add_f32 v[108:109], v[108:109], v[74:75]
	v_exp_f32_e32 v78, v78
	v_exp_f32_e32 v79, v79
	s_mov_b64 s[0:1], 0
	v_pk_add_f32 v[108:109], v[108:109], v[76:77]
	s_nop 0
	v_pk_add_f32 v[108:109], v[108:109], v[78:79]
	s_nop 0
	v_add_f32_e32 v107, v108, v109

.LBB0_1018:
	v_mul_f32_e32 v33, 0.5, v67
	ds_bpermute_b32 v33, v181, v33
	v_add_f32_e32 v35, v64, v65
	v_fma_f32 v36, 0.5, v67, v66
	v_add_f32_e32 v35, v35, v36
	v_add_u32_e32 v34, 0x13f80, v91
	s_waitcnt lgkmcnt(0)
	v_cndmask_b32_e64 v36, v33, v81, s[4:5]
	v_add_f32_e32 v35, v36, v35
	v_mul_f32_e32 v36, 0.5, v71
	ds_bpermute_b32 v36, v181, v36
	ds_write_b32 v34, v35
	v_add_f32_e32 v34, v68, v69
	v_fma_f32 v35, 0.5, v71, v70
	v_add_f32_e32 v34, v34, v35
	v_mul_f32_e32 v35, 0.5, v75
	ds_bpermute_b32 v35, v181, v35
	s_waitcnt lgkmcnt(2)
	v_cndmask_b32_e64 v33, v36, v33, s[4:5]
	v_add_f32_e32 v33, v34, v33
	v_add_u32_e32 v34, 0x13f90, v91
	ds_write_b32 v34, v33
	v_add_f32_e32 v33, v72, v73
	v_fma_f32 v34, 0.5, v75, v74
	v_add_f32_e32 v33, v33, v34
	s_waitcnt lgkmcnt(1)
	v_cndmask_b32_e64 v34, v35, v36, s[4:5]
	v_mul_f32_e32 v36, 0.5, v79
	ds_bpermute_b32 v81, v181, v36
	v_add_f32_e32 v33, v33, v34
	v_add_u32_e32 v34, 0x13fa0, v91
	ds_write_b32 v34, v33
	v_add_f32_e32 v33, v76, v77
	v_fma_f32 v34, 0.5, v79, v78
	v_add_f32_e32 v33, v33, v34
	s_waitcnt lgkmcnt(1)
	v_cndmask_b32_e64 v34, v81, v35, s[4:5]
	v_add_f32_e32 v33, v33, v34
	v_add_u32_e32 v34, 0x13fb0, v91
	v_add_f32_e32 v32, v80, v90
	ds_write_b32 v34, v33
	v_add_f32_e32 v80, v32, v107
	ds_read_b128 v[32:35], v92 offset:40960
	ds_read_b128 v[36:39], v92 offset:43520
	ds_read_b128 v[40:43], v92 offset:46080
	ds_read_b128 v[94:97], v92 offset:48640
	v_cvt_pk_bf16_f32 v64, v64, v65
	v_cvt_pk_bf16_f32 v65, v66, v67
	v_cvt_pk_bf16_f32 v66, v68, v69
	v_cvt_pk_bf16_f32 v67, v70, v71
	s_waitcnt lgkmcnt(3)
	v_mfma_f32_16x16x32_bf16 v[16:19], v[32:35], v[64:67], v[16:19]
	s_waitcnt lgkmcnt(2)
	v_mfma_f32_16x16x32_bf16 v[20:23], v[36:39], v[64:67], v[20:23]
	s_waitcnt lgkmcnt(1)
	v_mfma_f32_16x16x32_bf16 v[24:27], v[40:43], v[64:67], v[24:27]
	s_waitcnt lgkmcnt(0)
	v_mfma_f32_16x16x32_bf16 v[28:31], v[94:97], v[64:67], v[28:31]
	ds_read_b128 v[32:35], v92 offset:41024
	ds_read_b128 v[36:39], v92 offset:43584
	ds_read_b128 v[40:43], v92 offset:46144
	ds_read_b128 v[64:67], v92 offset:48704
	v_cvt_pk_bf16_f32 v90, v72, v73
	v_cvt_pk_bf16_f32 v91, v74, v75
	v_cvt_pk_bf16_f32 v92, v76, v77
	v_cvt_pk_bf16_f32 v93, v78, v79
	s_waitcnt lgkmcnt(3)
	v_mfma_f32_16x16x32_bf16 v[72:75], v[32:35], v[90:93], v[16:19]
	s_waitcnt lgkmcnt(2)
	v_mfma_f32_16x16x32_bf16 v[76:79], v[36:39], v[90:93], v[20:23]
	s_waitcnt lgkmcnt(1)
	v_mfma_f32_16x16x32_bf16 v[68:71], v[40:43], v[90:93], v[24:27]
	s_waitcnt lgkmcnt(0)
	v_mfma_f32_16x16x32_bf16 v[64:67], v[64:67], v[90:93], v[28:31]
	s_sub_i32 s0, s23, 64
	s_and_b32 s0, s0, 0x80
	s_mulk_i32 s0, 0xa0
	v_add_u32_e32 v16, s0, v151
	s_waitcnt vmcnt(3)
	ds_write_b128 v16, v[4:7]
	v_add_u32_e32 v4, s0, v152
	s_and_b32 s0, s23, 0xc0
	v_add_u32_e32 v4, 0xa000, v4
	s_mulk_i32 s0, 0xa0
	s_waitcnt vmcnt(2)
	ds_write2_b64 v4, v[0:1], v[2:3] offset1:2
	v_add_u32_e32 v0, s0, v151
	s_waitcnt vmcnt(1)
	ds_write_b128 v0, v[12:15]
	v_add_u32_e32 v0, s0, v152
	s_add_i32 s0, s24, -1
	s_min_i32 s0, s0, s21
	s_lshl_b32 s0, s0, 6
	s_ashr_i32 s1, s0, 31
	s_lshl_b64 s[26:27], s[0:1], 7
	v_lshl_add_u64 v[2:3], s[0:1], 1, v[46:47]
	s_min_i32 s0, s24, s21
	s_lshl_b32 s0, s0, 6
	v_add_u32_e32 v0, 0xa000, v0
	s_ashr_i32 s1, s0, 31
	s_waitcnt vmcnt(0)
	ds_write2_b64 v0, v[8:9], v[10:11] offset1:2
	s_add_i32 s98, s24, -1
	s_cmp_gt_i32 s98, s21
	s_cbranch_scc1 .Lcmp_skip_pf
	v_lshl_add_u64 v[0:1], v[44:45], 0, s[26:27]
	s_lshl_b64 s[26:27], s[0:1], 7
	global_load_dwordx4 v[4:7], v[0:1], off
	s_nop 0
	global_load_dwordx4 v[0:3], v[2:3], off
	v_lshl_add_u64 v[8:9], v[44:45], 0, s[26:27]
	v_lshl_add_u64 v[10:11], s[0:1], 1, v[46:47]
	global_load_dwordx4 v[12:15], v[8:9], off
	s_nop 0
	global_load_dwordx4 v[8:11], v[10:11], off

.LBB0_1021:
	s_cmp_ge_i32 s0, s20
	s_cbranch_scc1 .LBB0_1027
	s_lshl_b32 s21, s0, 6
	s_and_b32 s1, s21, 0x80
	s_mulk_i32 s1, 0xa0
	v_add_u32_e32 v28, s1, v153
	s_waitcnt vmcnt(2)
	ds_read_b128 v[0:3], v28
	ds_read_b128 v[4:7], v28 offset:64
	s_waitcnt vmcnt(0)
	ds_read_b128 v[8:11], v28 offset:2560
	ds_read_b128 v[12:15], v28 offset:2624
	ds_read_b128 v[16:19], v28 offset:5120
	ds_read_b128 v[20:23], v28 offset:5184
	ds_read_b128 v[24:27], v28 offset:7680
	ds_read_b128 v[30:33], v28 offset:7744
	v_sub_u32_e32 v29, v144, v150
	s_waitcnt lgkmcnt(7)
	v_mfma_f32_16x16x32_bf16 v[0:3], v[0:3], v[60:63], 0
	s_waitcnt lgkmcnt(6)
	v_mfma_f32_16x16x32_bf16 v[34:37], v[4:7], v[56:59], v[0:3]
	s_waitcnt lgkmcnt(5)
	v_mfma_f32_16x16x32_bf16 v[0:3], v[8:11], v[60:63], 0
	s_waitcnt lgkmcnt(4)
	v_mfma_f32_16x16x32_bf16 v[8:11], v[12:15], v[56:59], v[0:3]
	s_waitcnt lgkmcnt(3)
	v_mfma_f32_16x16x32_bf16 v[0:3], v[16:19], v[60:63], 0
	s_waitcnt lgkmcnt(2)
	v_mfma_f32_16x16x32_bf16 v[4:7], v[20:23], v[56:59], v[0:3]
	s_waitcnt lgkmcnt(1)
	v_mfma_f32_16x16x32_bf16 v[0:3], v[24:27], v[60:63], 0
	s_waitcnt lgkmcnt(0)
	v_mfma_f32_16x16x32_bf16 v[0:3], v[30:33], v[56:59], v[0:3]
	s_lshl_b32 s0, s0, 10
	v_subrev_u32_e32 v12, s0, v29
	v_subrev_u32_e32 v29, 31, v12
	v_cvt_f32_i32_e32 v12, v29
	s_or_b32 s0, s21, 63
	s_add_i32 s1, s75, -2
	v_mul_f32_e32 v13, 0x41800000, v146
	v_mul_f32_e32 v12, v146, v12
	v_fma_f32 v39, v146, 0, -v12
	v_mul_f32_e32 v14, 0x42000000, v146
	v_mul_f32_e32 v15, 0x42400000, v146
	v_fmamk_f32 v42, v34, 0x3e38aa3b, v39
	v_fmamk_f32 v40, v146, 0x41800000, v39
	v_fmamk_f32 v41, v146, 0x42000000, v39
	v_fmac_f32_e32 v39, 0x42400000, v146
	v_fma_f32 v16, v146, s67, -v12
	v_fma_f32 v17, v146, s68, -v12
	v_fma_f32 v12, v146, s69, -v12
	s_cmp_gt_i32 s0, s1
	v_fmac_f32_e32 v40, 0x3e38aa3b, v35
	v_fmac_f32_e32 v41, 0x3e38aa3b, v36
	v_fmac_f32_e32 v39, 0x3e38aa3b, v37
	s_mov_b64 s[0:1], -1
	v_fmamk_f32 v38, v8, 0x3e38aa3b, v16
	v_add_f32_e32 v37, v13, v16
	v_add_f32_e32 v36, v14, v16
	v_add_f32_e32 v35, v15, v16
	v_fmamk_f32 v34, v4, 0x3e38aa3b, v17
	v_add_f32_e32 v33, v13, v17
	v_add_f32_e32 v32, v14, v17
	v_add_f32_e32 v31, v15, v17
	v_fmamk_f32 v30, v0, 0x3e38aa3b, v12
	v_add_f32_e32 v8, v13, v12
	v_add_f32_e32 v4, v14, v12
	v_add_f32_e32 v0, v15, v12
	s_cbranch_scc1 .LBB0_1024
	v_mov_b32_e32 v12, v42
	v_mov_b32_e32 v13, v40
	v_mov_b32_e32 v14, v41
	v_mov_b32_e32 v15, v39
	v_exp_f32_e32 v12, v12
	v_exp_f32_e32 v13, v13
	v_fmamk_f32 v17, v9, 0x3e38aa3b, v37
	v_mov_b32_e32 v16, v38
	v_exp_f32_e32 v14, v14
	v_exp_f32_e32 v15, v15
	v_fmamk_f32 v18, v10, 0x3e38aa3b, v36
	v_fmamk_f32 v19, v11, 0x3e38aa3b, v35
	v_pk_add_f32 v[44:45], v[12:13], 0 op_sel_hi:[1,0]
	v_exp_f32_e32 v16, v16
	v_exp_f32_e32 v17, v17
	v_fmamk_f32 v21, v5, 0x3e38aa3b, v33
	v_mov_b32_e32 v20, v34
	v_pk_add_f32 v[44:45], v[44:45], v[14:15]
	v_exp_f32_e32 v18, v18
	v_exp_f32_e32 v19, v19
	v_fmamk_f32 v22, v6, 0x3e38aa3b, v32
	v_fmamk_f32 v23, v7, 0x3e38aa3b, v31
	v_pk_add_f32 v[44:45], v[44:45], v[16:17]
	v_exp_f32_e32 v20, v20
	v_exp_f32_e32 v21, v21
	v_fmamk_f32 v25, v1, 0x3e38aa3b, v8
	v_mov_b32_e32 v24, v30
	v_pk_add_f32 v[44:45], v[44:45], v[18:19]
	v_exp_f32_e32 v22, v22
	v_exp_f32_e32 v23, v23
	v_fmamk_f32 v26, v2, 0x3e38aa3b, v4
	v_fmamk_f32 v27, v3, 0x3e38aa3b, v0
	v_pk_add_f32 v[44:45], v[44:45], v[20:21]
	v_exp_f32_e32 v24, v24
	v_exp_f32_e32 v25, v25
	v_pk_add_f32 v[44:45], v[44:45], v[22:23]
	v_exp_f32_e32 v26, v26
	v_exp_f32_e32 v27, v27
	s_mov_b64 s[0:1], 0
	v_pk_add_f32 v[44:45], v[44:45], v[24:25]
	s_nop 0
	v_pk_add_f32 v[44:45], v[44:45], v[26:27]
	s_nop 0
	v_add_f32_e32 v43, v44, v45

.LBB0_1026:
	v_mul_f32_e32 v0, 0.5, v15
	ds_bpermute_b32 v0, v181, v0
	v_mul_f32_e32 v4, 0.5, v19
	ds_bpermute_b32 v4, v181, v4
	v_add_f32_e32 v2, v12, v13
	v_fma_f32 v3, 0.5, v15, v14
	v_add_f32_e32 v2, v2, v3
	s_waitcnt lgkmcnt(1)
	v_cndmask_b32_e64 v3, v0, v81, s[4:5]
	v_add_f32_e32 v2, v2, v3
	v_add_f32_e32 v3, v16, v17
	v_fma_f32 v5, 0.5, v19, v18
	v_add_f32_e32 v3, v3, v5
	s_waitcnt lgkmcnt(0)
	v_cndmask_b32_e64 v0, v4, v0, s[4:5]
	v_add_f32_e32 v0, v3, v0
	v_mul_f32_e32 v3, 0.5, v23
	ds_bpermute_b32 v3, v181, v3
	v_add_u32_e32 v1, s21, v155
	ds_write2_b32 v1, v2, v0 offset1:4
	v_add_f32_e32 v0, v20, v21
	v_fma_f32 v2, 0.5, v23, v22
	v_add_f32_e32 v0, v0, v2
	s_waitcnt lgkmcnt(1)
	v_cndmask_b32_e64 v2, v3, v4, s[4:5]
	v_mul_f32_e32 v4, 0.5, v27
	ds_bpermute_b32 v81, v181, v4
	v_add_f32_e32 v0, v0, v2
	v_add_f32_e32 v2, v24, v25
	v_fma_f32 v4, 0.5, v27, v26
	v_add_f32_e32 v2, v2, v4
	s_waitcnt lgkmcnt(0)
	v_cndmask_b32_e64 v3, v81, v3, s[4:5]
	v_add_f32_e32 v2, v2, v3
	ds_write2_b32 v1, v0, v2 offset0:8 offset1:12
	ds_read_b128 v[0:3], v28 offset:40960
	ds_read_b128 v[4:7], v28 offset:43520
	ds_read_b128 v[8:11], v28 offset:46080
	ds_read_b128 v[30:33], v28 offset:48640
	v_add_f32_e32 v80, v80, v43
	v_cvt_pk_bf16_f32 v12, v12, v13
	v_cvt_pk_bf16_f32 v13, v14, v15
	v_cvt_pk_bf16_f32 v14, v16, v17
	v_cvt_pk_bf16_f32 v15, v18, v19
	s_waitcnt lgkmcnt(3)
	v_mfma_f32_16x16x32_bf16 v[0:3], v[0:3], v[12:15], v[72:75]
	s_waitcnt lgkmcnt(2)
	v_mfma_f32_16x16x32_bf16 v[4:7], v[4:7], v[12:15], v[76:79]
	s_waitcnt lgkmcnt(1)
	v_mfma_f32_16x16x32_bf16 v[8:11], v[8:11], v[12:15], v[68:71]
	s_waitcnt lgkmcnt(0)
	v_mfma_f32_16x16x32_bf16 v[12:15], v[30:33], v[12:15], v[64:67]
	ds_read_b128 v[16:19], v28 offset:41024
	ds_read_b128 v[30:33], v28 offset:43584
	ds_read_b128 v[34:37], v28 offset:46144
	ds_read_b128 v[38:41], v28 offset:48704
	v_cvt_pk_bf16_f32 v20, v20, v21
	v_cvt_pk_bf16_f32 v21, v22, v23
	v_cvt_pk_bf16_f32 v22, v24, v25
	v_cvt_pk_bf16_f32 v23, v26, v27
	s_waitcnt lgkmcnt(3)
	v_mfma_f32_16x16x32_bf16 v[72:75], v[16:19], v[20:23], v[0:3]
	s_waitcnt lgkmcnt(2)
	v_mfma_f32_16x16x32_bf16 v[76:79], v[30:33], v[20:23], v[4:7]
	s_waitcnt lgkmcnt(1)
	v_mfma_f32_16x16x32_bf16 v[68:71], v[34:37], v[20:23], v[8:11]
	s_waitcnt lgkmcnt(0)
	v_mfma_f32_16x16x32_bf16 v[64:67], v[38:41], v[20:23], v[12:15]
	s_waitcnt lgkmcnt(0)
	s_barrier

.LBB0_1044:
	s_lshl_b32 s29, s22, 6
	v_subrev_u32_e32 v1, s29, v139
	s_add_i32 s29, s81, 0xffffff80
	s_and_b32 s29, s29, 0x80
	s_mulk_i32 s29, 0xa0
	v_add_u32_e32 v143, s29, v153
	ds_read_b128 v[88:91], v143
	ds_read_b128 v[92:95], v143 offset:64
	ds_read_b128 v[96:99], v143 offset:2560
	ds_read_b128 v[100:103], v143 offset:2624
	ds_read_b128 v[104:107], v143 offset:5120
	ds_read_b128 v[108:111], v143 offset:5184
	ds_read_b128 v[112:115], v143 offset:7680
	ds_read_b128 v[116:119], v143 offset:7744
	s_lshl_b32 s29, s23, 6
	v_subrev_u32_e32 v0, s29, v139
	s_max_i32 s22, s22, s23
	s_cmp_ge_i32 s22, s76
	v_cvt_f32_i32_e32 v147, v1
	v_cvt_f32_i32_e32 v141, v0
	s_mov_b64 s[22:23], -1
	s_cbranch_scc0 .LBB0_1046
	s_waitcnt lgkmcnt(7)
	v_mfma_f32_16x16x32_bf16 v[2:5], v[88:91], v[60:63], 0
	s_waitcnt lgkmcnt(5)
	v_mfma_f32_16x16x32_bf16 v[6:9], v[96:99], v[60:63], 0
	s_waitcnt lgkmcnt(3)
	v_mfma_f32_16x16x32_bf16 v[10:13], v[104:107], v[60:63], 0
	s_waitcnt lgkmcnt(1)
	v_mfma_f32_16x16x32_bf16 v[80:83], v[112:115], v[60:63], 0
	v_mfma_f32_16x16x32_bf16 v[2:5], v[92:95], v[56:59], v[2:5]
	v_mfma_f32_16x16x32_bf16 v[6:9], v[100:103], v[56:59], v[6:9]
	v_mfma_f32_16x16x32_bf16 v[10:13], v[108:111], v[56:59], v[10:13]
	s_waitcnt lgkmcnt(0)
	v_mfma_f32_16x16x32_bf16 v[80:83], v[116:119], v[56:59], v[80:83]
	v_fma_f32 v14, -v146, v147, v192
	s_nop 1
	v_fmamk_f32 v2, v2, 0x3e38aa3b, v14
	v_cmp_gt_u32_e32 vcc, s70, v1
	v_add_f32_e32 v15, v146, v14
	s_and_b64 vcc, vcc, s[20:21]
	v_fmac_f32_e32 v15, 0x3e38aa3b, v3
	v_add_f32_e32 v3, v137, v14
	v_cndmask_b32_e32 v2, v179, v2, vcc
	v_cmp_lt_i32_e32 vcc, 0, v1
	v_fmac_f32_e32 v3, 0x3e38aa3b, v4
	v_add_f32_e32 v4, v188, v14
	s_and_b64 vcc, vcc, s[20:21]
	v_add_u32_e32 v14, -2, v1
	v_fmac_f32_e32 v4, 0x3e38aa3b, v5
	s_nop 0
	v_cndmask_b32_e32 v5, v179, v15, vcc
	v_cmp_gt_u32_e32 vcc, s70, v14
	s_and_b64 vcc, s[20:21], vcc
	v_add_u32_e32 v14, -3, v1
	v_cndmask_b32_e32 v3, v179, v3, vcc
	v_cmp_gt_u32_e32 vcc, s70, v14
	v_exp_f32_e32 v14, v2
	v_fma_f32 v2, -v146, v147, v189
	s_and_b64 vcc, s[20:21], vcc
	v_exp_f32_e32 v193, v3
	v_fmamk_f32 v3, v6, 0x3e38aa3b, v2
	v_add_u32_e32 v6, -16, v1
	v_cndmask_b32_e32 v4, v179, v4, vcc
	v_cmp_gt_u32_e32 vcc, s70, v6
	v_exp_f32_e32 v195, v4
	v_add_f32_e32 v4, v146, v2
	s_and_b64 vcc, s[20:21], vcc
	v_subrev_u32_e32 v6, 17, v1
	v_fmac_f32_e32 v4, 0x3e38aa3b, v7
	v_cndmask_b32_e32 v3, v179, v3, vcc
	v_cmp_gt_u32_e32 vcc, s70, v6
	v_exp_f32_e32 v15, v5
	v_add_f32_e32 v5, v137, v2
	s_and_b64 vcc, vcc, s[20:21]
	v_subrev_u32_e32 v6, 18, v1
	v_fmac_f32_e32 v5, 0x3e38aa3b, v8
	v_cndmask_b32_e32 v4, v179, v4, vcc
	v_cmp_gt_u32_e32 vcc, s70, v6
	v_add_f32_e32 v2, v188, v2
	s_and_b64 vcc, s[20:21], vcc
	v_subrev_u32_e32 v6, 19, v1
	v_fmac_f32_e32 v2, 0x3e38aa3b, v9
	v_cndmask_b32_e32 v5, v179, v5, vcc
	v_cmp_gt_u32_e32 vcc, s70, v6
	s_and_b64 vcc, s[20:21], vcc
	v_subrev_u32_e32 v6, 32, v1
	v_cndmask_b32_e32 v2, v179, v2, vcc
	v_exp_f32_e32 v199, v2
	v_fma_f32 v2, -v146, v147, v190
	v_exp_f32_e32 v196, v3
	v_fmamk_f32 v3, v10, 0x3e38aa3b, v2
	v_cmp_gt_u32_e32 vcc, s70, v6
	v_exp_f32_e32 v197, v4
	v_add_f32_e32 v4, v146, v2
	s_and_b64 vcc, s[20:21], vcc
	v_subrev_u32_e32 v6, 33, v1
	v_fmac_f32_e32 v4, 0x3e38aa3b, v11
	v_cndmask_b32_e32 v3, v179, v3, vcc
	v_cmp_gt_u32_e32 vcc, s70, v6
	v_exp_f32_e32 v198, v5
	v_add_f32_e32 v5, v137, v2
	s_and_b64 vcc, vcc, s[20:21]
	v_subrev_u32_e32 v6, 34, v1
	v_fmac_f32_e32 v5, 0x3e38aa3b, v12
	v_cndmask_b32_e32 v4, v179, v4, vcc
	v_cmp_gt_u32_e32 vcc, s70, v6
	v_add_f32_e32 v2, v188, v2
	s_and_b64 vcc, s[20:21], vcc
	v_subrev_u32_e32 v6, 35, v1
	v_fmac_f32_e32 v2, 0x3e38aa3b, v13
	v_cndmask_b32_e32 v5, v179, v5, vcc
	v_cmp_gt_u32_e32 vcc, s70, v6
	s_and_b64 vcc, s[20:21], vcc
	v_subrev_u32_e32 v6, 48, v1
	v_cndmask_b32_e32 v2, v179, v2, vcc
	v_exp_f32_e32 v221, v2
	v_fma_f32 v2, -v146, v147, v191
	v_exp_f32_e32 v218, v3
	v_fmamk_f32 v3, v80, 0x3e38aa3b, v2
	v_cmp_gt_u32_e32 vcc, s70, v6
	v_exp_f32_e32 v219, v4
	v_add_f32_e32 v4, v146, v2
	s_and_b64 vcc, s[20:21], vcc
	v_subrev_u32_e32 v6, 49, v1
	v_fmac_f32_e32 v4, 0x3e38aa3b, v81
	v_cndmask_b32_e32 v3, v179, v3, vcc
	v_cmp_gt_u32_e32 vcc, s70, v6
	v_exp_f32_e32 v220, v5
	v_add_f32_e32 v5, v137, v2
	s_and_b64 vcc, vcc, s[20:21]
	v_subrev_u32_e32 v6, 50, v1
	v_fmac_f32_e32 v5, 0x3e38aa3b, v82
	v_cndmask_b32_e32 v4, v179, v4, vcc
	v_cmp_gt_u32_e32 vcc, s70, v6
	v_add_f32_e32 v2, v188, v2
	s_and_b64 vcc, s[20:21], vcc
	v_subrev_u32_e32 v1, 51, v1
	v_fmac_f32_e32 v2, 0x3e38aa3b, v83
	v_cndmask_b32_e32 v5, v179, v5, vcc
	v_cmp_gt_u32_e32 vcc, s70, v1
	s_and_b64 vcc, s[20:21], vcc
	v_exp_f32_e32 v222, v3
	v_cndmask_b32_e32 v1, v179, v2, vcc
	v_exp_f32_e32 v223, v4
	v_exp_f32_e32 v224, v5
	ds_read_b128 v[2:5], v143 offset:40960
	ds_read_b128 v[6:9], v143 offset:43520
	ds_read_b128 v[10:13], v143 offset:46080
	ds_read_b128 v[80:83], v143 offset:48640
	v_exp_f32_e32 v1, v1
	s_nop 0
	v_cvt_pk_bf16_f32 v194, v14, v15
	v_cvt_pk_bf16_f32 v195, v193, v195
	v_cvt_pk_bf16_f32 v196, v196, v197
	v_cvt_pk_bf16_f32 v197, v198, v199
	s_mov_b32 s30, s28
	s_mov_b32 s31, s28
	s_waitcnt lgkmcnt(0)
	v_mfma_f32_16x16x32_bf16 v[198:201], v[80:83], v[194:197], v[84:87]
	s_mov_b32 s29, s28
	v_mov_b64_e32 v[82:83], s[30:31]
	v_mov_b64_e32 v[80:81], s[28:29]
	v_mfma_f32_16x16x32_bf16 v[2:5], v[2:5], v[194:197], v[36:39]
	v_mfma_f32_16x16x32_bf16 v[6:9], v[6:9], v[194:197], v[40:43]
	v_mfma_f32_16x16x32_bf16 v[10:13], v[10:13], v[194:197], v[44:47]
	v_mfma_f32_16x16x32_bf16 v[194:197], v[80:83], v[194:197], v[32:35]
	ds_read_b128 v[202:205], v143 offset:41024
	ds_read_b128 v[206:209], v143 offset:43584
	ds_read_b128 v[210:213], v143 offset:46144
	ds_read_b128 v[214:217], v143 offset:48704
	v_cvt_pk_bf16_f32 v218, v218, v219
	v_cvt_pk_bf16_f32 v219, v220, v221
	v_cvt_pk_bf16_f32 v220, v222, v223
	v_cvt_pk_bf16_f32 v221, v224, v1
	s_waitcnt lgkmcnt(3)
	v_mfma_f32_16x16x32_bf16 v[2:5], v[202:205], v[218:221], v[2:5]
	s_waitcnt lgkmcnt(2)
	v_mfma_f32_16x16x32_bf16 v[6:9], v[206:209], v[218:221], v[6:9]
	s_waitcnt lgkmcnt(1)
	v_mfma_f32_16x16x32_bf16 v[10:13], v[210:213], v[218:221], v[10:13]
	s_waitcnt lgkmcnt(0)
	v_mfma_f32_16x16x32_bf16 v[198:201], v[214:217], v[218:221], v[198:201]
	v_mfma_f32_16x16x32_bf16 v[194:197], v[80:83], v[218:221], v[194:197]
	s_sub_i32 s22, s81, 64
	s_and_b32 s22, s22, 0xc0
	s_mulk_i32 s22, 0xa0
	v_add_u32_e32 v193, s22, v153
	ds_read_b128 v[202:205], v193
	ds_read_b128 v[206:209], v193 offset:64
	ds_read_b128 v[210:213], v193 offset:2560
	ds_read_b128 v[214:217], v193 offset:2624
	ds_read_b128 v[218:221], v193 offset:5120
	ds_read_b128 v[222:225], v193 offset:5184
	ds_read_b128 v[226:229], v193 offset:7680
	ds_read_b128 v[230:233], v193 offset:7744
	s_waitcnt lgkmcnt(7)
	v_mfma_f32_16x16x32_bf16 v[202:205], v[202:205], v[60:63], 0
	s_waitcnt lgkmcnt(6)
	v_mfma_f32_16x16x32_bf16 v[202:205], v[206:209], v[56:59], v[202:205]
	s_waitcnt lgkmcnt(5)
	v_mfma_f32_16x16x32_bf16 v[206:209], v[210:213], v[60:63], 0
	s_waitcnt lgkmcnt(4)
	v_mfma_f32_16x16x32_bf16 v[206:209], v[214:217], v[56:59], v[206:209]
	s_waitcnt lgkmcnt(3)
	v_mfma_f32_16x16x32_bf16 v[210:213], v[218:221], v[60:63], 0
	s_waitcnt lgkmcnt(1)
	v_mfma_f32_16x16x32_bf16 v[214:217], v[226:229], v[60:63], 0
	v_mfma_f32_16x16x32_bf16 v[210:213], v[222:225], v[56:59], v[210:213]
	s_waitcnt lgkmcnt(0)
	v_mfma_f32_16x16x32_bf16 v[214:217], v[230:233], v[56:59], v[214:217]
	v_fma_f32 v1, -v146, v141, v192
	v_fmamk_f32 v14, v202, 0x3e38aa3b, v1
	v_cmp_gt_u32_e32 vcc, s70, v0
	v_add_f32_e32 v15, v146, v1
	s_and_b64 vcc, vcc, s[0:1]
	v_fmac_f32_e32 v15, 0x3e38aa3b, v203
	v_cndmask_b32_e32 v14, v179, v14, vcc
	v_cmp_lt_i32_e32 vcc, 0, v0
	v_add_f32_e32 v202, v137, v1
	s_and_b64 vcc, vcc, s[0:1]
	v_add_u32_e32 v203, -2, v0
	v_fmac_f32_e32 v202, 0x3e38aa3b, v204
	v_cndmask_b32_e32 v15, v179, v15, vcc
	v_cmp_gt_u32_e32 vcc, s70, v203
	s_and_b64 vcc, s[0:1], vcc
	v_add_f32_e32 v1, v188, v1
	v_cndmask_b32_e32 v202, v179, v202, vcc
	v_add_u32_e32 v203, -3, v0
	v_fmac_f32_e32 v1, 0x3e38aa3b, v205
	v_cmp_gt_u32_e32 vcc, s70, v203
	v_exp_f32_e32 v219, v202
	v_fma_f32 v202, -v146, v141, v189
	s_and_b64 vcc, s[0:1], vcc
	v_fmamk_f32 v203, v206, 0x3e38aa3b, v202
	v_add_u32_e32 v206, -16, v0
	v_cndmask_b32_e32 v1, v179, v1, vcc
	v_cmp_gt_u32_e32 vcc, s70, v206
	v_add_f32_e32 v204, v146, v202
	s_and_b64 vcc, s[0:1], vcc
	v_subrev_u32_e32 v206, 17, v0
	v_fmac_f32_e32 v204, 0x3e38aa3b, v207
	v_cndmask_b32_e32 v203, v179, v203, vcc
	v_cmp_gt_u32_e32 vcc, s70, v206
	v_add_f32_e32 v205, v137, v202
	s_and_b64 vcc, vcc, s[0:1]
	v_subrev_u32_e32 v206, 18, v0
	v_fmac_f32_e32 v205, 0x3e38aa3b, v208
	v_cndmask_b32_e32 v204, v179, v204, vcc
	v_cmp_gt_u32_e32 vcc, s70, v206
	v_add_f32_e32 v202, v188, v202
	s_and_b64 vcc, s[0:1], vcc
	v_subrev_u32_e32 v206, 19, v0
	v_fmac_f32_e32 v202, 0x3e38aa3b, v209
	v_cndmask_b32_e32 v205, v179, v205, vcc
	v_cmp_gt_u32_e32 vcc, s70, v206
	s_and_b64 vcc, s[0:1], vcc
	v_subrev_u32_e32 v206, 32, v0
	v_cndmask_b32_e32 v202, v179, v202, vcc
	v_exp_f32_e32 v223, v202
	v_fma_f32 v202, -v146, v141, v190
	v_exp_f32_e32 v220, v203
	v_fmamk_f32 v203, v210, 0x3e38aa3b, v202
	v_cmp_gt_u32_e32 vcc, s70, v206
	v_exp_f32_e32 v221, v204
	v_add_f32_e32 v204, v146, v202
	s_and_b64 vcc, s[0:1], vcc
	v_subrev_u32_e32 v206, 33, v0
	v_fmac_f32_e32 v204, 0x3e38aa3b, v211
	v_cndmask_b32_e32 v203, v179, v203, vcc
	v_cmp_gt_u32_e32 vcc, s70, v206
	v_exp_f32_e32 v222, v205
	v_add_f32_e32 v205, v137, v202
	s_and_b64 vcc, vcc, s[0:1]
	v_subrev_u32_e32 v206, 34, v0
	v_fmac_f32_e32 v205, 0x3e38aa3b, v212
	v_cndmask_b32_e32 v204, v179, v204, vcc
	v_cmp_gt_u32_e32 vcc, s70, v206
	v_add_f32_e32 v202, v188, v202
	s_and_b64 vcc, s[0:1], vcc
	v_subrev_u32_e32 v206, 35, v0
	v_fmac_f32_e32 v202, 0x3e38aa3b, v213
	v_cndmask_b32_e32 v205, v179, v205, vcc
	v_cmp_gt_u32_e32 vcc, s70, v206
	s_and_b64 vcc, s[0:1], vcc
	v_subrev_u32_e32 v206, 48, v0
	v_cndmask_b32_e32 v202, v179, v202, vcc
	v_exp_f32_e32 v227, v202
	v_fma_f32 v202, -v146, v141, v191
	v_exp_f32_e32 v224, v203
	v_fmamk_f32 v203, v214, 0x3e38aa3b, v202
	v_cmp_gt_u32_e32 vcc, s70, v206
	v_exp_f32_e32 v225, v204
	v_add_f32_e32 v204, v146, v202
	s_and_b64 vcc, s[0:1], vcc
	v_subrev_u32_e32 v206, 49, v0
	v_fmac_f32_e32 v204, 0x3e38aa3b, v215
	v_cndmask_b32_e32 v203, v179, v203, vcc
	v_cmp_gt_u32_e32 vcc, s70, v206
	v_exp_f32_e32 v226, v205
	v_add_f32_e32 v205, v137, v202
	s_and_b64 vcc, vcc, s[0:1]
	v_subrev_u32_e32 v206, 50, v0
	v_fmac_f32_e32 v205, 0x3e38aa3b, v216
	v_cndmask_b32_e32 v204, v179, v204, vcc
	v_cmp_gt_u32_e32 vcc, s70, v206
	v_add_f32_e32 v202, v188, v202
	s_and_b64 vcc, s[0:1], vcc
	v_subrev_u32_e32 v0, 51, v0
	v_fmac_f32_e32 v202, 0x3e38aa3b, v217
	v_cndmask_b32_e32 v205, v179, v205, vcc
	v_cmp_gt_u32_e32 vcc, s70, v0
	s_and_b64 vcc, s[0:1], vcc
	v_exp_f32_e32 v228, v203
	v_cndmask_b32_e32 v0, v179, v202, vcc
	v_exp_f32_e32 v229, v204
	v_exp_f32_e32 v230, v205
	ds_read_b128 v[202:205], v193 offset:40960
	ds_read_b128 v[206:209], v193 offset:43520
	ds_read_b128 v[210:213], v193 offset:46080
	ds_read_b128 v[214:217], v193 offset:48640
	v_exp_f32_e32 v14, v14
	v_exp_f32_e32 v15, v15
	v_exp_f32_e32 v1, v1
	v_exp_f32_e32 v231, v0
	s_nop 0
	v_cvt_pk_bf16_f32 v218, v14, v15
	v_cvt_pk_bf16_f32 v219, v219, v1
	v_cvt_pk_bf16_f32 v220, v220, v221
	v_cvt_pk_bf16_f32 v221, v222, v223
	s_waitcnt lgkmcnt(3)
	v_mfma_f32_16x16x32_bf16 v[0:3], v[202:205], v[218:221], v[2:5]
	s_waitcnt lgkmcnt(2)
	v_mfma_f32_16x16x32_bf16 v[4:7], v[206:209], v[218:221], v[6:9]
	s_waitcnt lgkmcnt(1)
	v_mfma_f32_16x16x32_bf16 v[8:11], v[210:213], v[218:221], v[10:13]
	s_waitcnt lgkmcnt(0)
	v_mfma_f32_16x16x32_bf16 v[12:15], v[214:217], v[218:221], v[198:201]
	v_mfma_f32_16x16x32_bf16 v[194:197], v[80:83], v[218:221], v[194:197]
	s_nop 0
	ds_read_b128 v[198:201], v193 offset:41024
	ds_read_b128 v[202:205], v193 offset:43584
	ds_read_b128 v[206:209], v193 offset:46144
	ds_read_b128 v[210:213], v193 offset:48704
	v_cvt_pk_bf16_f32 v214, v224, v225
	v_cvt_pk_bf16_f32 v215, v226, v227
	v_cvt_pk_bf16_f32 v216, v228, v229
	v_cvt_pk_bf16_f32 v217, v230, v231
	s_waitcnt lgkmcnt(3)
	v_mfma_f32_16x16x32_bf16 v[0:3], v[198:201], v[214:217], v[0:3]
	s_mov_b64 s[22:23], 0
	s_waitcnt lgkmcnt(2)
	v_mfma_f32_16x16x32_bf16 v[4:7], v[202:205], v[214:217], v[4:7]
	s_waitcnt lgkmcnt(1)
	v_mfma_f32_16x16x32_bf16 v[8:11], v[206:209], v[214:217], v[8:11]
	s_waitcnt lgkmcnt(0)
	v_mfma_f32_16x16x32_bf16 v[12:15], v[210:213], v[214:217], v[12:15]
	v_mfma_f32_16x16x32_bf16 v[80:83], v[80:83], v[214:217], v[194:197]
.LBB0_1046:
	s_andn2_b64 vcc, exec, s[22:23]
	s_cbranch_vccnz .LBB0_1048
	s_waitcnt lgkmcnt(7)
	v_mfma_f32_16x16x32_bf16 v[0:3], v[88:91], v[60:63], 0
	s_waitcnt lgkmcnt(5)
	v_mfma_f32_16x16x32_bf16 v[4:7], v[96:99], v[60:63], 0
	s_waitcnt lgkmcnt(3)
	v_mfma_f32_16x16x32_bf16 v[8:11], v[104:107], v[60:63], 0
	s_waitcnt lgkmcnt(1)
	v_mfma_f32_16x16x32_bf16 v[12:15], v[112:115], v[60:63], 0
	v_mfma_f32_16x16x32_bf16 v[0:3], v[92:95], v[56:59], v[0:3]
	v_mfma_f32_16x16x32_bf16 v[4:7], v[100:103], v[56:59], v[4:7]
	v_mfma_f32_16x16x32_bf16 v[8:11], v[108:111], v[56:59], v[8:11]
	s_waitcnt lgkmcnt(0)
	v_mfma_f32_16x16x32_bf16 v[12:15], v[116:119], v[56:59], v[12:15]
	v_mul_f32_e64 v80, -v146, v147
	v_cndmask_b32_e64 v80, v179, v80, s[20:21]
	v_add_f32_e32 v81, v192, v80
	v_add_f32_e32 v82, v146, v81
	v_fmac_f32_e32 v82, 0x3e38aa3b, v1
	v_add_f32_e32 v1, v137, v81
	v_fmamk_f32 v0, v0, 0x3e38aa3b, v81
	v_fmac_f32_e32 v1, 0x3e38aa3b, v2
	v_add_f32_e32 v2, v188, v81
	v_fmac_f32_e32 v2, 0x3e38aa3b, v3
	s_nop 0
	v_exp_f32_e32 v81, v0
	v_add_f32_e32 v0, v189, v80
	v_exp_f32_e32 v83, v1
	v_exp_f32_e32 v88, v2
	v_fmamk_f32 v1, v4, 0x3e38aa3b, v0
	v_add_f32_e32 v2, v146, v0
	v_add_f32_e32 v3, v137, v0
	v_add_f32_e32 v0, v188, v0
	v_fmac_f32_e32 v0, 0x3e38aa3b, v7
	v_fmac_f32_e32 v2, 0x3e38aa3b, v5
	v_fmac_f32_e32 v3, 0x3e38aa3b, v6
	v_exp_f32_e32 v82, v82
	v_exp_f32_e32 v92, v0
	v_add_f32_e32 v0, v190, v80
	v_exp_f32_e32 v89, v1
	v_exp_f32_e32 v90, v2
	v_exp_f32_e32 v91, v3
	v_fmamk_f32 v1, v8, 0x3e38aa3b, v0
	v_add_f32_e32 v2, v146, v0
	v_add_f32_e32 v3, v137, v0
	v_add_f32_e32 v0, v188, v0
	v_fmac_f32_e32 v0, 0x3e38aa3b, v11
	v_fmac_f32_e32 v2, 0x3e38aa3b, v9
	v_fmac_f32_e32 v3, 0x3e38aa3b, v10
	s_nop 0
	v_exp_f32_e32 v96, v0
	v_add_f32_e32 v0, v191, v80
	v_exp_f32_e32 v93, v1
	v_exp_f32_e32 v94, v2
	v_exp_f32_e32 v95, v3
	v_fmamk_f32 v1, v12, 0x3e38aa3b, v0
	v_add_f32_e32 v2, v146, v0
	v_add_f32_e32 v3, v137, v0
	v_add_f32_e32 v0, v188, v0
	v_fmac_f32_e32 v2, 0x3e38aa3b, v13
	v_fmac_f32_e32 v3, 0x3e38aa3b, v14
	v_fmac_f32_e32 v0, 0x3e38aa3b, v15
	s_nop 0
	v_exp_f32_e32 v97, v1
	v_exp_f32_e32 v98, v2
	v_exp_f32_e32 v99, v3
	v_exp_f32_e32 v100, v0
	ds_read_b128 v[0:3], v143 offset:40960
	ds_read_b128 v[4:7], v143 offset:43520
	ds_read_b128 v[8:11], v143 offset:46080
	ds_read_b128 v[12:15], v143 offset:48640
	v_cvt_pk_bf16_f32 v80, v81, v82
	v_cvt_pk_bf16_f32 v81, v83, v88
	v_cvt_pk_bf16_f32 v82, v89, v90
	v_cvt_pk_bf16_f32 v83, v91, v92
	s_mov_b32 s30, s28
	s_mov_b32 s31, s28
	s_waitcnt lgkmcnt(3)
	v_mfma_f32_16x16x32_bf16 v[0:3], v[0:3], v[80:83], v[36:39]
	s_mov_b32 s29, s28
	s_nop 1
	v_mov_b64_e32 v[38:39], s[30:31]
	v_mov_b64_e32 v[36:37], s[28:29]
	s_waitcnt lgkmcnt(2)
	v_mfma_f32_16x16x32_bf16 v[4:7], v[4:7], v[80:83], v[40:43]
	s_waitcnt lgkmcnt(1)
	v_mfma_f32_16x16x32_bf16 v[8:11], v[8:11], v[80:83], v[44:47]
	s_waitcnt lgkmcnt(0)
	v_mfma_f32_16x16x32_bf16 v[12:15], v[12:15], v[80:83], v[84:87]
	v_mfma_f32_16x16x32_bf16 v[32:35], v[36:39], v[80:83], v[32:35]
	ds_read_b128 v[40:43], v143 offset:41024
	ds_read_b128 v[44:47], v143 offset:43584
	ds_read_b128 v[80:83], v143 offset:46144
	ds_read_b128 v[84:87], v143 offset:48704
	v_cvt_pk_bf16_f32 v88, v93, v94
	v_cvt_pk_bf16_f32 v89, v95, v96
	v_cvt_pk_bf16_f32 v90, v97, v98
	v_cvt_pk_bf16_f32 v91, v99, v100
	s_waitcnt lgkmcnt(3)
	v_mfma_f32_16x16x32_bf16 v[0:3], v[40:43], v[88:91], v[0:3]
	s_waitcnt lgkmcnt(2)
	v_mfma_f32_16x16x32_bf16 v[4:7], v[44:47], v[88:91], v[4:7]
	s_waitcnt lgkmcnt(1)
	v_mfma_f32_16x16x32_bf16 v[8:11], v[80:83], v[88:91], v[8:11]
	s_waitcnt lgkmcnt(0)
	v_mfma_f32_16x16x32_bf16 v[12:15], v[84:87], v[88:91], v[12:15]
	v_mfma_f32_16x16x32_bf16 v[32:35], v[36:39], v[88:91], v[32:35]
	s_sub_i32 s20, s81, 64
	s_and_b32 s20, s20, 0xc0
	s_mulk_i32 s20, 0xa0
	v_add_u32_e32 v104, s20, v153
	ds_read_b128 v[40:43], v104
	ds_read_b128 v[44:47], v104 offset:64
	ds_read_b128 v[80:83], v104 offset:2560
	ds_read_b128 v[84:87], v104 offset:2624
	ds_read_b128 v[88:91], v104 offset:5120
	ds_read_b128 v[92:95], v104 offset:5184
	ds_read_b128 v[96:99], v104 offset:7680
	ds_read_b128 v[100:103], v104 offset:7744
	s_waitcnt lgkmcnt(7)
	v_mfma_f32_16x16x32_bf16 v[40:43], v[40:43], v[60:63], 0
	s_waitcnt lgkmcnt(6)
	v_mfma_f32_16x16x32_bf16 v[40:43], v[44:47], v[56:59], v[40:43]
	s_waitcnt lgkmcnt(5)
	v_mfma_f32_16x16x32_bf16 v[44:47], v[80:83], v[60:63], 0
	s_waitcnt lgkmcnt(3)
	v_mfma_f32_16x16x32_bf16 v[80:83], v[88:91], v[60:63], 0
	v_mfma_f32_16x16x32_bf16 v[44:47], v[84:87], v[56:59], v[44:47]
	s_waitcnt lgkmcnt(2)
	v_mfma_f32_16x16x32_bf16 v[80:83], v[92:95], v[56:59], v[80:83]
	s_waitcnt lgkmcnt(1)
	v_mfma_f32_16x16x32_bf16 v[84:87], v[96:99], v[60:63], 0
	s_waitcnt lgkmcnt(0)
	v_mfma_f32_16x16x32_bf16 v[84:87], v[100:103], v[56:59], v[84:87]
	v_mul_f32_e64 v88, -v146, v141
	v_cndmask_b32_e64 v88, v179, v88, s[0:1]
	v_add_f32_e32 v89, v192, v88
	v_add_f32_e32 v90, v146, v89
	v_fmac_f32_e32 v90, 0x3e38aa3b, v41
	v_add_f32_e32 v41, v137, v89
	v_fmamk_f32 v40, v40, 0x3e38aa3b, v89
	v_fmac_f32_e32 v41, 0x3e38aa3b, v42
	v_add_f32_e32 v42, v188, v89
	v_fmac_f32_e32 v42, 0x3e38aa3b, v43
	s_nop 0
	v_exp_f32_e32 v89, v40
	v_add_f32_e32 v40, v189, v88
	v_exp_f32_e32 v91, v41
	v_exp_f32_e32 v92, v42
	v_fmamk_f32 v41, v44, 0x3e38aa3b, v40
	v_add_f32_e32 v42, v146, v40
	v_add_f32_e32 v43, v137, v40
	v_add_f32_e32 v40, v188, v40
	v_fmac_f32_e32 v40, 0x3e38aa3b, v47
	v_fmac_f32_e32 v42, 0x3e38aa3b, v45
	v_fmac_f32_e32 v43, 0x3e38aa3b, v46
	v_exp_f32_e32 v90, v90
	v_exp_f32_e32 v96, v40
	v_add_f32_e32 v40, v190, v88
	v_exp_f32_e32 v93, v41
	v_exp_f32_e32 v94, v42
	v_exp_f32_e32 v95, v43
	v_fmamk_f32 v41, v80, 0x3e38aa3b, v40
	v_add_f32_e32 v42, v146, v40
	v_add_f32_e32 v43, v137, v40
	v_add_f32_e32 v40, v188, v40
	v_fmac_f32_e32 v40, 0x3e38aa3b, v83
	v_fmac_f32_e32 v42, 0x3e38aa3b, v81
	v_fmac_f32_e32 v43, 0x3e38aa3b, v82
	s_nop 0
	v_exp_f32_e32 v100, v40
	v_add_f32_e32 v40, v191, v88
	v_exp_f32_e32 v97, v41
	v_exp_f32_e32 v98, v42
	v_exp_f32_e32 v99, v43
	v_fmamk_f32 v41, v84, 0x3e38aa3b, v40
	v_add_f32_e32 v42, v146, v40
	v_add_f32_e32 v43, v137, v40
	v_add_f32_e32 v40, v188, v40
	v_fmac_f32_e32 v42, 0x3e38aa3b, v85
	v_fmac_f32_e32 v43, 0x3e38aa3b, v86
	v_fmac_f32_e32 v40, 0x3e38aa3b, v87
	s_nop 0
	v_exp_f32_e32 v101, v41
	v_exp_f32_e32 v102, v42
	v_exp_f32_e32 v103, v43
	v_exp_f32_e32 v105, v40
	ds_read_b128 v[40:43], v104 offset:40960
	ds_read_b128 v[44:47], v104 offset:43520
	ds_read_b128 v[80:83], v104 offset:46080
	ds_read_b128 v[84:87], v104 offset:48640
	v_cvt_pk_bf16_f32 v88, v89, v90
	v_cvt_pk_bf16_f32 v89, v91, v92
	v_cvt_pk_bf16_f32 v90, v93, v94
	v_cvt_pk_bf16_f32 v91, v95, v96
	s_waitcnt lgkmcnt(3)
	v_mfma_f32_16x16x32_bf16 v[0:3], v[40:43], v[88:91], v[0:3]
	s_waitcnt lgkmcnt(2)
	v_mfma_f32_16x16x32_bf16 v[4:7], v[44:47], v[88:91], v[4:7]
	s_waitcnt lgkmcnt(1)
	v_mfma_f32_16x16x32_bf16 v[8:11], v[80:83], v[88:91], v[8:11]
	s_waitcnt lgkmcnt(0)
	v_mfma_f32_16x16x32_bf16 v[12:15], v[84:87], v[88:91], v[12:15]
	v_mfma_f32_16x16x32_bf16 v[32:35], v[36:39], v[88:91], v[32:35]
	ds_read_b128 v[40:43], v104 offset:41024
	ds_read_b128 v[44:47], v104 offset:43584
	ds_read_b128 v[80:83], v104 offset:46144
	ds_read_b128 v[84:87], v104 offset:48704
	v_cvt_pk_bf16_f32 v88, v97, v98
	v_cvt_pk_bf16_f32 v89, v99, v100
	v_cvt_pk_bf16_f32 v90, v101, v102
	v_cvt_pk_bf16_f32 v91, v103, v105
	s_waitcnt lgkmcnt(3)
	v_mfma_f32_16x16x32_bf16 v[0:3], v[40:43], v[88:91], v[0:3]
	s_waitcnt lgkmcnt(2)
	v_mfma_f32_16x16x32_bf16 v[4:7], v[44:47], v[88:91], v[4:7]
	s_waitcnt lgkmcnt(1)
	v_mfma_f32_16x16x32_bf16 v[8:11], v[80:83], v[88:91], v[8:11]
	s_waitcnt lgkmcnt(0)
	v_mfma_f32_16x16x32_bf16 v[12:15], v[84:87], v[88:91], v[12:15]
	v_mfma_f32_16x16x32_bf16 v[80:83], v[36:39], v[88:91], v[32:35]

.LBB0_1054:
	s_lshl_b32 s20, s20, 6
	s_and_b32 s20, s20, 0x80
	s_mulk_i32 s20, 0xa0
	v_add_u32_e32 v104, s20, v153
	ds_read_b128 v[84:87], v104
	ds_read_b128 v[88:91], v104 offset:64
	ds_read_b128 v[92:95], v104 offset:2560
	ds_read_b128 v[96:99], v104 offset:2624
	ds_read_b128 v[32:35], v104 offset:5120
	ds_read_b128 v[36:39], v104 offset:5184
	ds_read_b128 v[40:43], v104 offset:7680
	ds_read_b128 v[44:47], v104 offset:7744
	v_lshl_or_b32 v16, s21, 6, v124
	v_sub_u32_e32 v16, v144, v16
	s_cmp_ge_i32 s21, s76
	v_cvt_f32_i32_e32 v143, v16
	s_cbranch_scc0 .LBB0_1056
	s_waitcnt lgkmcnt(7)
	v_mfma_f32_16x16x32_bf16 v[18:21], v[84:87], v[60:63], 0
	s_waitcnt vmcnt(0) lgkmcnt(5)
	v_mfma_f32_16x16x32_bf16 v[22:25], v[92:95], v[60:63], 0
	s_waitcnt lgkmcnt(3)
	v_mfma_f32_16x16x32_bf16 v[26:29], v[32:35], v[60:63], 0
	s_waitcnt lgkmcnt(1)
	v_mfma_f32_16x16x32_bf16 v[100:103], v[40:43], v[60:63], 0
	v_mfma_f32_16x16x32_bf16 v[18:21], v[88:91], v[56:59], v[18:21]
	v_mfma_f32_16x16x32_bf16 v[22:25], v[96:99], v[56:59], v[22:25]
	v_mfma_f32_16x16x32_bf16 v[26:29], v[36:39], v[56:59], v[26:29]
	s_waitcnt lgkmcnt(0)
	v_mfma_f32_16x16x32_bf16 v[100:103], v[44:47], v[56:59], v[100:103]
	v_add_u32_e32 v17, -2, v16
	v_cmp_gt_u32_e64 s[20:21], s70, v17
	v_add_u32_e32 v17, -3, v16
	v_pk_mul_f32 v[30:31], v[146:147], v[142:143] op_sel_hi:[0,1]
	v_cmp_gt_u32_e64 s[22:23], s70, v17
	v_fma_f32 v17, v146, 0, -v31
	v_cmp_gt_u32_e32 vcc, s70, v16
	v_fmamk_f32 v18, v18, 0x3e38aa3b, v17
	v_cmp_lt_i32_e64 s[0:1], 0, v16
	v_add_f32_e32 v105, v146, v17
	s_and_b64 vcc, vcc, s[26:27]
	v_fmac_f32_e32 v105, 0x3e38aa3b, v19
	v_cndmask_b32_e32 v18, v179, v18, vcc
	s_and_b64 vcc, s[0:1], s[26:27]
	v_mov_b32_e32 v147, v24
	v_cndmask_b32_e32 v19, v179, v105, vcc
	v_exp_f32_e32 v105, v18
	v_exp_f32_e32 v106, v19
	v_sub_f32_e32 v30, v30, v31
	v_pk_mul_f32 v[18:19], v[146:147], s[44:45]
	v_fmamk_f32 v107, v22, 0x3e38aa3b, v30
	v_add_f32_e32 v22, v18, v17
	v_fmac_f32_e32 v22, 0x3e38aa3b, v20
	v_add_f32_e32 v108, v146, v30
	s_and_b64 vcc, s[26:27], s[20:21]
	v_mov_b32_e32 v147, v25
	s_mov_b32 s47, s45
	v_fmac_f32_e32 v108, 0x3e38aa3b, v23
	v_cndmask_b32_e32 v20, v179, v22, vcc
	v_pk_mul_f32 v[22:23], v[146:147], s[46:47]
	v_exp_f32_e32 v109, v20
	v_add_f32_e32 v17, v22, v17
	v_add_f32_e32 v20, v18, v30
	v_fmac_f32_e32 v17, 0x3e38aa3b, v21
	v_add_f32_e32 v19, v20, v19
	s_and_b64 vcc, s[26:27], s[22:23]
	v_add_u32_e32 v20, -16, v16
	v_cndmask_b32_e32 v17, v179, v17, vcc
	v_cmp_gt_u32_e32 vcc, s70, v20
	s_and_b64 vcc, s[26:27], vcc
	v_subrev_u32_e32 v21, 17, v16
	v_exp_f32_e32 v110, v17
	v_add_f32_e32 v17, v22, v30
	v_add_f32_e32 v17, v17, v23
	v_cndmask_b32_e32 v20, v179, v107, vcc
	v_cmp_gt_u32_e32 vcc, s70, v21
	s_and_b64 vcc, vcc, s[26:27]
	v_subrev_u32_e32 v23, 18, v16
	v_exp_f32_e32 v107, v20
	v_cndmask_b32_e32 v21, v179, v108, vcc
	v_cmp_gt_u32_e32 vcc, s70, v23
	s_and_b64 vcc, s[26:27], vcc
	v_subrev_u32_e32 v23, 19, v16
	v_cndmask_b32_e32 v19, v179, v19, vcc
	v_cmp_gt_u32_e32 vcc, s70, v23
	s_and_b64 vcc, s[26:27], vcc
	v_subrev_u32_e32 v23, 32, v16
	v_cndmask_b32_e32 v17, v179, v17, vcc
	v_exp_f32_e32 v112, v17
	v_fma_f32 v17, v146, s65, -v31
	v_exp_f32_e32 v111, v19
	v_fmamk_f32 v19, v26, 0x3e38aa3b, v17
	v_cmp_gt_u32_e32 vcc, s70, v23
	v_add_f32_e32 v20, v146, v17
	s_and_b64 vcc, s[26:27], vcc
	v_subrev_u32_e32 v23, 33, v16
	v_fmac_f32_e32 v20, 0x3e38aa3b, v27
	v_cndmask_b32_e32 v19, v179, v19, vcc
	v_cmp_gt_u32_e32 vcc, s70, v23
	v_exp_f32_e32 v108, v21
	v_add_f32_e32 v21, v18, v17
	s_and_b64 vcc, vcc, s[26:27]
	v_subrev_u32_e32 v23, 34, v16
	v_fmac_f32_e32 v21, 0x3e38aa3b, v28
	v_cndmask_b32_e32 v20, v179, v20, vcc
	v_cmp_gt_u32_e32 vcc, s70, v23
	v_add_f32_e32 v17, v22, v17
	s_and_b64 vcc, s[26:27], vcc
	v_subrev_u32_e32 v23, 35, v16
	v_fmac_f32_e32 v17, 0x3e38aa3b, v29
	v_cndmask_b32_e32 v21, v179, v21, vcc
	v_cmp_gt_u32_e32 vcc, s70, v23
	s_and_b64 vcc, s[26:27], vcc
	v_exp_f32_e32 v139, v21
	v_cndmask_b32_e32 v17, v179, v17, vcc
	v_exp_f32_e32 v141, v17
	v_fma_f32 v17, v146, s66, -v31
	v_subrev_u32_e32 v21, 48, v16
	v_exp_f32_e32 v118, v19
	v_fmamk_f32 v19, v100, 0x3e38aa3b, v17
	v_cmp_gt_u32_e32 vcc, s70, v21
	v_exp_f32_e32 v119, v20
	v_add_f32_e32 v20, v146, v17
	s_and_b64 vcc, s[26:27], vcc
	v_subrev_u32_e32 v21, 49, v16
	v_fmac_f32_e32 v20, 0x3e38aa3b, v101
	v_cndmask_b32_e32 v19, v179, v19, vcc
	v_cmp_gt_u32_e32 vcc, s70, v21
	v_add_f32_e32 v18, v18, v17
	s_and_b64 vcc, vcc, s[26:27]
	v_subrev_u32_e32 v21, 50, v16
	v_fmac_f32_e32 v18, 0x3e38aa3b, v102
	v_cndmask_b32_e32 v20, v179, v20, vcc
	v_cmp_gt_u32_e32 vcc, s70, v21
	s_and_b64 vcc, s[26:27], vcc
	v_subrev_u32_e32 v16, 51, v16
	v_add_f32_e32 v17, v22, v17
	v_cndmask_b32_e32 v18, v179, v18, vcc
	v_cmp_gt_u32_e32 vcc, s70, v16
	v_fmac_f32_e32 v17, 0x3e38aa3b, v103
	s_and_b64 vcc, s[26:27], vcc
	v_exp_f32_e32 v147, v19
	v_cndmask_b32_e32 v16, v179, v17, vcc
	v_exp_f32_e32 v148, v20
	v_exp_f32_e32 v149, v18
	v_exp_f32_e32 v193, v16
	ds_read_b128 v[16:19], v104 offset:40960
	ds_read_b128 v[20:23], v104 offset:43520
	ds_read_b128 v[24:27], v104 offset:46080
	ds_read_b128 v[28:31], v104 offset:48640
	s_nop 0
	v_cvt_pk_bf16_f32 v100, v105, v106
	v_cvt_pk_bf16_f32 v101, v109, v110
	v_cvt_pk_bf16_f32 v102, v107, v108
	v_cvt_pk_bf16_f32 v103, v111, v112
	s_mov_b32 s30, s28
	s_mov_b32 s31, s28
	s_mov_b32 s29, s28
	v_mov_b64_e32 v[108:109], s[30:31]
	v_mov_b64_e32 v[106:107], s[28:29]
	s_waitcnt lgkmcnt(3)
	v_mfma_f32_16x16x32_bf16 v[16:19], v[16:19], v[100:103], v[0:3]
	s_waitcnt lgkmcnt(2)
	v_mfma_f32_16x16x32_bf16 v[20:23], v[20:23], v[100:103], v[4:7]
	s_waitcnt lgkmcnt(1)
	v_mfma_f32_16x16x32_bf16 v[24:27], v[24:27], v[100:103], v[8:11]
	s_waitcnt lgkmcnt(0)
	v_mfma_f32_16x16x32_bf16 v[28:31], v[28:31], v[100:103], v[12:15]
	v_mfma_f32_16x16x32_bf16 v[100:103], v[106:109], v[100:103], v[80:83]
	ds_read_b128 v[110:113], v104 offset:41024
	ds_read_b128 v[114:117], v104 offset:43584
	ds_read_b128 v[194:197], v104 offset:46144
	ds_read_b128 v[198:201], v104 offset:48704
	v_cvt_pk_bf16_f32 v202, v118, v119
	v_cvt_pk_bf16_f32 v203, v139, v141
	v_cvt_pk_bf16_f32 v204, v147, v148
	v_cvt_pk_bf16_f32 v205, v149, v193
	s_waitcnt lgkmcnt(3)
	v_mfma_f32_16x16x32_bf16 v[16:19], v[110:113], v[202:205], v[16:19]
	s_mov_b64 s[0:1], 0
	s_waitcnt lgkmcnt(2)
	v_mfma_f32_16x16x32_bf16 v[20:23], v[114:117], v[202:205], v[20:23]
	s_waitcnt lgkmcnt(1)
	v_mfma_f32_16x16x32_bf16 v[24:27], v[194:197], v[202:205], v[24:27]
	s_waitcnt lgkmcnt(0)
	v_mfma_f32_16x16x32_bf16 v[28:31], v[198:201], v[202:205], v[28:31]
	v_mfma_f32_16x16x32_bf16 v[100:103], v[106:109], v[202:205], v[100:103]
.LBB0_1056:
	s_andn2_b64 vcc, exec, s[0:1]
	s_cbranch_vccnz .LBB0_1058
	s_waitcnt lgkmcnt(7)
	v_mfma_f32_16x16x32_bf16 v[16:19], v[84:87], v[60:63], 0
	s_waitcnt lgkmcnt(5)
	v_mfma_f32_16x16x32_bf16 v[20:23], v[92:95], v[60:63], 0
	s_waitcnt vmcnt(0) lgkmcnt(3)
	v_mfma_f32_16x16x32_bf16 v[24:27], v[32:35], v[60:63], 0
	s_waitcnt lgkmcnt(1)
	v_mfma_f32_16x16x32_bf16 v[28:31], v[40:43], v[60:63], 0
	v_mfma_f32_16x16x32_bf16 v[16:19], v[88:91], v[56:59], v[16:19]
	v_mfma_f32_16x16x32_bf16 v[20:23], v[96:99], v[56:59], v[20:23]
	v_mfma_f32_16x16x32_bf16 v[24:27], v[36:39], v[56:59], v[24:27]
	s_waitcnt lgkmcnt(0)
	v_mfma_f32_16x16x32_bf16 v[28:31], v[44:47], v[56:59], v[28:31]
	v_mul_f32_e64 v32, -v146, v143
	v_cndmask_b32_e64 v32, v179, v32, s[26:27]
	v_fma_f32 v33, 0, v146, v32
	v_fmamk_f32 v16, v16, 0x3e38aa3b, v33
	v_add_f32_e32 v34, v146, v33
	v_mov_b32_e32 v147, v22
	v_fmac_f32_e32 v34, 0x3e38aa3b, v17
	v_exp_f32_e32 v35, v16
	v_fmamk_f32 v36, v146, 0x41800000, v32
	v_pk_mul_f32 v[16:17], v[146:147], s[44:45]
	v_fmamk_f32 v37, v20, 0x3e38aa3b, v36
	v_add_f32_e32 v20, v16, v33
	v_fmac_f32_e32 v20, 0x3e38aa3b, v18
	v_add_f32_e32 v38, v146, v36
	v_mov_b32_e32 v147, v23
	s_mov_b32 s47, s45
	v_fmac_f32_e32 v38, 0x3e38aa3b, v21
	v_exp_f32_e32 v39, v20
	v_add_f32_e32 v18, v16, v36
	v_pk_mul_f32 v[20:21], v[146:147], s[46:47]
	v_add_f32_e32 v17, v18, v17
	v_add_f32_e32 v18, v20, v33
	v_fmac_f32_e32 v18, 0x3e38aa3b, v19
	s_nop 0
	v_exp_f32_e32 v33, v18
	v_add_f32_e32 v18, v20, v36
	v_add_f32_e32 v18, v18, v21
	v_exp_f32_e32 v36, v37
	v_exp_f32_e32 v37, v38
	v_exp_f32_e32 v38, v17
	v_fmamk_f32 v17, v146, 0x42000000, v32
	v_add_f32_e32 v19, v146, v17
	v_exp_f32_e32 v40, v18
	v_fmamk_f32 v18, v24, 0x3e38aa3b, v17
	v_fmac_f32_e32 v19, 0x3e38aa3b, v25
	v_add_f32_e32 v21, v16, v17
	v_add_f32_e32 v17, v20, v17
	v_fmac_f32_e32 v17, 0x3e38aa3b, v27
	v_fmac_f32_e32 v32, 0x42400000, v146
	v_exp_f32_e32 v41, v18
	v_exp_f32_e32 v42, v19
	v_add_f32_e32 v18, v146, v32
	v_add_f32_e32 v16, v16, v32
	v_add_f32_e32 v19, v20, v32
	v_fmac_f32_e32 v21, 0x3e38aa3b, v26
	v_exp_f32_e32 v44, v17
	v_fmamk_f32 v17, v28, 0x3e38aa3b, v32
	v_fmac_f32_e32 v18, 0x3e38aa3b, v29
	v_fmac_f32_e32 v16, 0x3e38aa3b, v30
	v_fmac_f32_e32 v19, 0x3e38aa3b, v31
	v_exp_f32_e32 v34, v34
	v_exp_f32_e32 v43, v21
	v_exp_f32_e32 v45, v17
	v_exp_f32_e32 v46, v18
	v_exp_f32_e32 v47, v16
	v_exp_f32_e32 v84, v19
	ds_read_b128 v[16:19], v104 offset:40960
	ds_read_b128 v[20:23], v104 offset:43520
	ds_read_b128 v[24:27], v104 offset:46080
	ds_read_b128 v[28:31], v104 offset:48640
	s_nop 0
	v_cvt_pk_bf16_f32 v32, v35, v34
	v_cvt_pk_bf16_f32 v33, v39, v33
	v_cvt_pk_bf16_f32 v34, v36, v37
	v_cvt_pk_bf16_f32 v35, v38, v40
	s_mov_b32 s30, s28
	s_mov_b32 s31, s28
	s_mov_b32 s29, s28
	v_mov_b64_e32 v[38:39], s[30:31]
	v_mov_b64_e32 v[36:37], s[28:29]
	s_waitcnt lgkmcnt(3)
	v_mfma_f32_16x16x32_bf16 v[0:3], v[16:19], v[32:35], v[0:3]
	s_waitcnt lgkmcnt(2)
	v_mfma_f32_16x16x32_bf16 v[4:7], v[20:23], v[32:35], v[4:7]
	s_waitcnt lgkmcnt(1)
	v_mfma_f32_16x16x32_bf16 v[8:11], v[24:27], v[32:35], v[8:11]
	s_waitcnt lgkmcnt(0)
	v_mfma_f32_16x16x32_bf16 v[12:15], v[28:31], v[32:35], v[12:15]
	v_mfma_f32_16x16x32_bf16 v[32:35], v[36:39], v[32:35], v[80:83]
	ds_read_b128 v[16:19], v104 offset:41024
	ds_read_b128 v[20:23], v104 offset:43584
	ds_read_b128 v[24:27], v104 offset:46144
	ds_read_b128 v[28:31], v104 offset:48704
	v_cvt_pk_bf16_f32 v40, v41, v42
	v_cvt_pk_bf16_f32 v41, v43, v44
	v_cvt_pk_bf16_f32 v42, v45, v46
	v_cvt_pk_bf16_f32 v43, v47, v84
	s_waitcnt lgkmcnt(3)
	v_mfma_f32_16x16x32_bf16 v[16:19], v[16:19], v[40:43], v[0:3]
	s_waitcnt lgkmcnt(2)
	v_mfma_f32_16x16x32_bf16 v[20:23], v[20:23], v[40:43], v[4:7]
	s_waitcnt lgkmcnt(1)
	v_mfma_f32_16x16x32_bf16 v[24:27], v[24:27], v[40:43], v[8:11]
	s_waitcnt lgkmcnt(0)
	v_mfma_f32_16x16x32_bf16 v[28:31], v[28:31], v[40:43], v[12:15]
	v_mfma_f32_16x16x32_bf16 v[100:103], v[36:39], v[40:43], v[32:35]
.LBB0_1058:
	s_waitcnt lgkmcnt(0)
	s_barrier
	s_waitcnt vmcnt(0)
	v_mov_b64_e32 v[0:1], v[16:17]
	s_nop 3
	v_mov_b64_e32 v[80:81], v[100:101]
	v_mov_b64_e32 v[2:3], v[18:19]
	v_mov_b64_e32 v[4:5], v[20:21]
	v_mov_b64_e32 v[6:7], v[22:23]
	v_mov_b64_e32 v[8:9], v[24:25]
	v_mov_b64_e32 v[10:11], v[26:27]
	v_mov_b64_e32 v[12:13], v[28:29]
	v_mov_b64_e32 v[14:15], v[30:31]
	v_mov_b64_e32 v[82:83], v[102:103]

.LBB0_1061:
	s_add_i32 s26, s20, s24
	s_add_i32 s0, s26, 63
	s_cmp_gt_i32 s0, s74
	s_cselect_b64 s[0:1], -1, 0
	s_cmp_lt_i32 s26, s22
	s_cselect_b64 s[30:31], -1, 0
	s_or_b64 s[0:1], s[0:1], s[30:31]
	v_add_u32_e32 v109, 0x73, v81
	v_add_u32_e32 v108, 51, v81
	s_add_i32 s25, s24, 64
	s_and_b64 vcc, exec, s[0:1]
	s_cbranch_vccnz .LBB0_1064
	s_add_i32 s27, s26, 64
	s_addk_i32 s26, 0x7f
	s_cmp_le_i32 s26, s74
	s_cselect_b64 s[0:1], -1, 0
	s_cmp_ge_i32 s27, s22
	s_cselect_b64 s[26:27], -1, 0
	s_and_b64 s[26:27], s[26:27], s[0:1]
	s_mov_b64 s[0:1], -1
	s_and_b64 vcc, exec, s[26:27]
	s_cbranch_vccz .LBB0_1064
	s_and_b32 s0, s24, 0x80
	s_mulk_i32 s0, 0xa0
	v_add_u32_e32 v118, s0, v153
	ds_read_b128 v[16:19], v118
	ds_read_b128 v[20:23], v118 offset:64
	ds_read_b128 v[24:27], v118 offset:2560
	ds_read_b128 v[28:31], v118 offset:2624
	ds_read_b128 v[82:85], v118 offset:5120
	ds_read_b128 v[110:113], v118 offset:5184
	ds_read_b128 v[114:117], v118 offset:7680
	ds_read_b128 v[194:197], v118 offset:7744
	s_waitcnt lgkmcnt(7)
	v_mfma_f32_16x16x32_bf16 v[16:19], v[16:19], v[60:63], 0
	s_waitcnt lgkmcnt(6)
	v_mfma_f32_16x16x32_bf16 v[16:19], v[20:23], v[56:59], v[16:19]
	s_waitcnt lgkmcnt(5)
	v_mfma_f32_16x16x32_bf16 v[20:23], v[24:27], v[60:63], 0
	s_waitcnt lgkmcnt(4)
	v_mfma_f32_16x16x32_bf16 v[20:23], v[28:31], v[56:59], v[20:23]
	s_waitcnt lgkmcnt(3)
	v_mfma_f32_16x16x32_bf16 v[24:27], v[82:85], v[60:63], 0
	s_waitcnt lgkmcnt(1)
	v_mfma_f32_16x16x32_bf16 v[28:31], v[114:117], v[60:63], 0
	v_mfma_f32_16x16x32_bf16 v[24:27], v[110:113], v[56:59], v[24:27]
	s_waitcnt lgkmcnt(0)
	v_mfma_f32_16x16x32_bf16 v[28:31], v[194:197], v[56:59], v[28:31]
	v_cvt_f32_i32_e32 v82, v109
	v_fma_f32 v83, -v146, v82, v192
	v_add_f32_e32 v84, v146, v83
	v_fmamk_f32 v16, v16, 0x3e38aa3b, v83
	v_fmac_f32_e32 v84, 0x3e38aa3b, v17
	v_add_f32_e32 v17, v188, v83
	v_fmac_f32_e32 v17, 0x3e38aa3b, v19
	v_add_f32_e32 v85, v137, v83
	v_exp_f32_e32 v83, v16
	v_fma_f32 v16, -v146, v82, v189
	v_fmac_f32_e32 v85, 0x3e38aa3b, v18
	v_exp_f32_e32 v110, v17
	v_fmamk_f32 v17, v20, 0x3e38aa3b, v16
	v_add_f32_e32 v18, v146, v16
	v_add_f32_e32 v19, v137, v16
	v_add_f32_e32 v16, v188, v16
	v_fmac_f32_e32 v16, 0x3e38aa3b, v23
	v_fmac_f32_e32 v18, 0x3e38aa3b, v21
	v_fmac_f32_e32 v19, 0x3e38aa3b, v22
	s_nop 0
	v_exp_f32_e32 v114, v16
	v_fma_f32 v16, -v146, v82, v190
	v_exp_f32_e32 v111, v17
	v_exp_f32_e32 v112, v18
	v_exp_f32_e32 v113, v19
	v_fmamk_f32 v17, v24, 0x3e38aa3b, v16
	v_add_f32_e32 v18, v146, v16
	v_add_f32_e32 v19, v137, v16
	v_add_f32_e32 v16, v188, v16
	v_fmac_f32_e32 v16, 0x3e38aa3b, v27
	v_fmac_f32_e32 v18, 0x3e38aa3b, v25
	v_fmac_f32_e32 v19, 0x3e38aa3b, v26
	v_exp_f32_e32 v84, v84
	v_exp_f32_e32 v143, v16
	v_fma_f32 v16, -v146, v82, v191
	v_exp_f32_e32 v119, v17
	v_exp_f32_e32 v139, v18
	v_exp_f32_e32 v141, v19
	v_fmamk_f32 v17, v28, 0x3e38aa3b, v16
	v_add_f32_e32 v18, v146, v16
	v_add_f32_e32 v19, v137, v16
	v_add_f32_e32 v16, v188, v16
	v_fmac_f32_e32 v18, 0x3e38aa3b, v29
	v_fmac_f32_e32 v19, 0x3e38aa3b, v30
	v_fmac_f32_e32 v16, 0x3e38aa3b, v31
	v_exp_f32_e32 v85, v85
	v_exp_f32_e32 v147, v17
	v_exp_f32_e32 v148, v18
	v_exp_f32_e32 v149, v19
	v_exp_f32_e32 v186, v16
	ds_read_b128 v[16:19], v118 offset:40960
	ds_read_b128 v[20:23], v118 offset:43520
	ds_read_b128 v[24:27], v118 offset:46080
	ds_read_b128 v[28:31], v118 offset:48640
	s_nop 0
	v_cvt_pk_bf16_f32 v82, v83, v84
	v_cvt_pk_bf16_f32 v83, v85, v110
	v_cvt_pk_bf16_f32 v84, v111, v112
	v_cvt_pk_bf16_f32 v85, v113, v114
	s_mov_b32 s30, s28
	s_mov_b32 s31, s28
	s_mov_b32 s29, s28
	v_mov_b64_e32 v[112:113], s[30:31]
	v_mov_b64_e32 v[110:111], s[28:29]
	s_waitcnt lgkmcnt(3)
	v_mfma_f32_16x16x32_bf16 v[16:19], v[16:19], v[82:85], v[90:93]
	s_waitcnt lgkmcnt(2)
	v_mfma_f32_16x16x32_bf16 v[20:23], v[20:23], v[82:85], v[94:97]
	s_waitcnt lgkmcnt(1)
	v_mfma_f32_16x16x32_bf16 v[24:27], v[24:27], v[82:85], v[98:101]
	s_waitcnt lgkmcnt(0)
	v_mfma_f32_16x16x32_bf16 v[28:31], v[28:31], v[82:85], v[102:105]
	v_mfma_f32_16x16x32_bf16 v[82:85], v[110:113], v[82:85], v[86:89]
	ds_read_b128 v[114:117], v118 offset:41024
	ds_read_b128 v[194:197], v118 offset:43584
	ds_read_b128 v[198:201], v118 offset:46144
	ds_read_b128 v[202:205], v118 offset:48704
	v_cvt_pk_bf16_f32 v206, v119, v139
	v_cvt_pk_bf16_f32 v207, v141, v143
	v_cvt_pk_bf16_f32 v208, v147, v148
	v_cvt_pk_bf16_f32 v209, v149, v186
	s_waitcnt lgkmcnt(3)
	v_mfma_f32_16x16x32_bf16 v[16:19], v[114:117], v[206:209], v[16:19]
	s_waitcnt lgkmcnt(2)
	v_mfma_f32_16x16x32_bf16 v[20:23], v[194:197], v[206:209], v[20:23]
	s_waitcnt lgkmcnt(1)
	v_mfma_f32_16x16x32_bf16 v[24:27], v[198:201], v[206:209], v[24:27]
	s_waitcnt lgkmcnt(0)
	v_mfma_f32_16x16x32_bf16 v[28:31], v[202:205], v[206:209], v[28:31]
	v_mfma_f32_16x16x32_bf16 v[82:85], v[110:113], v[206:209], v[82:85]
	s_and_b32 s0, s25, 0xc0
	s_mulk_i32 s0, 0xa0
	v_add_u32_e32 v118, s0, v153
	ds_read_b128 v[114:117], v118
	ds_read_b128 v[194:197], v118 offset:64
	ds_read_b128 v[198:201], v118 offset:2560
	ds_read_b128 v[202:205], v118 offset:2624
	ds_read_b128 v[206:209], v118 offset:5120
	ds_read_b128 v[210:213], v118 offset:5184
	ds_read_b128 v[214:217], v118 offset:7680
	ds_read_b128 v[218:221], v118 offset:7744
	s_waitcnt lgkmcnt(7)
	v_mfma_f32_16x16x32_bf16 v[114:117], v[114:117], v[60:63], 0
	s_waitcnt lgkmcnt(6)
	v_mfma_f32_16x16x32_bf16 v[114:117], v[194:197], v[56:59], v[114:117]
	s_waitcnt lgkmcnt(5)
	v_mfma_f32_16x16x32_bf16 v[194:197], v[198:201], v[60:63], 0
	s_waitcnt lgkmcnt(4)
	v_mfma_f32_16x16x32_bf16 v[194:197], v[202:205], v[56:59], v[194:197]
	s_waitcnt lgkmcnt(3)
	v_mfma_f32_16x16x32_bf16 v[198:201], v[206:209], v[60:63], 0
	s_waitcnt lgkmcnt(1)
	v_mfma_f32_16x16x32_bf16 v[202:205], v[214:217], v[60:63], 0
	v_mfma_f32_16x16x32_bf16 v[198:201], v[210:213], v[56:59], v[198:201]
	s_waitcnt lgkmcnt(0)
	v_mfma_f32_16x16x32_bf16 v[202:205], v[218:221], v[56:59], v[202:205]
	v_cvt_f32_i32_e32 v119, v108
	v_fma_f32 v139, -v146, v119, v192
	v_add_f32_e32 v141, v146, v139
	v_fmamk_f32 v114, v114, 0x3e38aa3b, v139
	v_fmac_f32_e32 v141, 0x3e38aa3b, v115
	v_add_f32_e32 v115, v188, v139
	v_fmac_f32_e32 v115, 0x3e38aa3b, v117
	v_add_f32_e32 v143, v137, v139
	v_exp_f32_e32 v139, v114
	v_fma_f32 v114, -v146, v119, v189
	v_fmac_f32_e32 v143, 0x3e38aa3b, v116
	v_exp_f32_e32 v147, v115
	v_fmamk_f32 v115, v194, 0x3e38aa3b, v114
	v_add_f32_e32 v116, v146, v114
	v_add_f32_e32 v117, v137, v114
	v_add_f32_e32 v114, v188, v114
	v_fmac_f32_e32 v114, 0x3e38aa3b, v197
	v_fmac_f32_e32 v116, 0x3e38aa3b, v195
	v_fmac_f32_e32 v117, 0x3e38aa3b, v196
	s_nop 0
	v_exp_f32_e32 v187, v114
	v_fma_f32 v114, -v146, v119, v190
	v_exp_f32_e32 v148, v115
	v_exp_f32_e32 v149, v116
	v_exp_f32_e32 v186, v117
	v_fmamk_f32 v115, v198, 0x3e38aa3b, v114
	v_add_f32_e32 v116, v146, v114
	v_add_f32_e32 v117, v137, v114
	v_add_f32_e32 v114, v188, v114
	v_fmac_f32_e32 v114, 0x3e38aa3b, v201
	v_fmac_f32_e32 v116, 0x3e38aa3b, v199
	v_fmac_f32_e32 v117, 0x3e38aa3b, v200
	v_exp_f32_e32 v141, v141
	v_exp_f32_e32 v212, v114
	v_fma_f32 v114, -v146, v119, v191
	v_exp_f32_e32 v193, v115
	v_exp_f32_e32 v210, v116
	v_exp_f32_e32 v211, v117
	v_fmamk_f32 v115, v202, 0x3e38aa3b, v114
	v_add_f32_e32 v116, v146, v114
	v_add_f32_e32 v117, v137, v114
	v_add_f32_e32 v114, v188, v114
	v_fmac_f32_e32 v116, 0x3e38aa3b, v203
	v_fmac_f32_e32 v117, 0x3e38aa3b, v204
	v_fmac_f32_e32 v114, 0x3e38aa3b, v205
	v_exp_f32_e32 v143, v143
	v_exp_f32_e32 v119, v115
	v_exp_f32_e32 v213, v116
	v_exp_f32_e32 v214, v117
	v_exp_f32_e32 v215, v114
	ds_read_b128 v[114:117], v118 offset:40960
	ds_read_b128 v[194:197], v118 offset:43520
	ds_read_b128 v[198:201], v118 offset:46080
	ds_read_b128 v[202:205], v118 offset:48640
	s_nop 0
	v_cvt_pk_bf16_f32 v206, v139, v141
	v_cvt_pk_bf16_f32 v207, v143, v147
	v_cvt_pk_bf16_f32 v208, v148, v149
	v_cvt_pk_bf16_f32 v209, v186, v187
	s_waitcnt lgkmcnt(3)
	v_mfma_f32_16x16x32_bf16 v[16:19], v[114:117], v[206:209], v[16:19]
	s_waitcnt lgkmcnt(2)
	v_mfma_f32_16x16x32_bf16 v[20:23], v[194:197], v[206:209], v[20:23]
	s_waitcnt lgkmcnt(1)
	v_mfma_f32_16x16x32_bf16 v[24:27], v[198:201], v[206:209], v[24:27]
	s_waitcnt lgkmcnt(0)
	v_mfma_f32_16x16x32_bf16 v[28:31], v[202:205], v[206:209], v[28:31]
	v_mfma_f32_16x16x32_bf16 v[82:85], v[110:113], v[206:209], v[82:85]
	ds_read_b128 v[114:117], v118 offset:41024
	ds_read_b128 v[194:197], v118 offset:43584
	ds_read_b128 v[198:201], v118 offset:46144
	ds_read_b128 v[202:205], v118 offset:48704
	v_cvt_pk_bf16_f32 v206, v193, v210
	v_cvt_pk_bf16_f32 v207, v211, v212
	v_cvt_pk_bf16_f32 v208, v119, v213
	v_cvt_pk_bf16_f32 v209, v214, v215
	s_waitcnt lgkmcnt(3)
	v_mfma_f32_16x16x32_bf16 v[16:19], v[114:117], v[206:209], v[16:19]
	s_mov_b64 s[0:1], 0
	s_waitcnt lgkmcnt(2)
	v_mfma_f32_16x16x32_bf16 v[20:23], v[194:197], v[206:209], v[20:23]
	s_waitcnt lgkmcnt(1)
	v_mfma_f32_16x16x32_bf16 v[24:27], v[198:201], v[206:209], v[24:27]
	s_waitcnt lgkmcnt(0)
	v_mfma_f32_16x16x32_bf16 v[28:31], v[202:205], v[206:209], v[28:31]
	v_mfma_f32_16x16x32_bf16 v[82:85], v[110:113], v[206:209], v[82:85]
.LBB0_1064:
	s_and_b64 vcc, exec, s[0:1]
	s_cbranch_vccz .LBB0_1066
	s_and_b32 s0, s24, 0x80
	s_mulk_i32 s0, 0xa0
	v_add_u32_e32 v118, s0, v153
	ds_read_b128 v[16:19], v118
	ds_read_b128 v[20:23], v118 offset:64
	ds_read_b128 v[24:27], v118 offset:2560
	ds_read_b128 v[28:31], v118 offset:2624
	ds_read_b128 v[82:85], v118 offset:5120
	ds_read_b128 v[110:113], v118 offset:5184
	ds_read_b128 v[114:117], v118 offset:7680
	ds_read_b128 v[194:197], v118 offset:7744
	s_waitcnt lgkmcnt(7)
	v_mfma_f32_16x16x32_bf16 v[16:19], v[16:19], v[60:63], 0
	s_waitcnt lgkmcnt(6)
	v_mfma_f32_16x16x32_bf16 v[16:19], v[20:23], v[56:59], v[16:19]
	s_waitcnt lgkmcnt(5)
	v_mfma_f32_16x16x32_bf16 v[20:23], v[24:27], v[60:63], 0
	s_waitcnt lgkmcnt(4)
	v_mfma_f32_16x16x32_bf16 v[20:23], v[28:31], v[56:59], v[20:23]
	s_waitcnt lgkmcnt(3)
	v_mfma_f32_16x16x32_bf16 v[24:27], v[82:85], v[60:63], 0
	s_waitcnt lgkmcnt(1)
	v_mfma_f32_16x16x32_bf16 v[28:31], v[114:117], v[60:63], 0
	v_mfma_f32_16x16x32_bf16 v[24:27], v[110:113], v[56:59], v[24:27]
	s_waitcnt lgkmcnt(0)
	v_mfma_f32_16x16x32_bf16 v[28:31], v[194:197], v[56:59], v[28:31]
	v_cvt_f32_i32_e32 v82, v109
	v_cmp_gt_u32_e32 vcc, s71, v109
	v_fma_f32 v83, -v146, v82, v192
	v_fmamk_f32 v16, v16, 0x3e38aa3b, v83
	v_add_f32_e32 v84, v146, v83
	v_add_f32_e32 v85, v137, v83
	v_fmac_f32_e32 v84, 0x3e38aa3b, v17
	v_fmac_f32_e32 v85, 0x3e38aa3b, v18
	v_add_f32_e32 v17, v188, v83
	v_add_u32_e32 v18, 0x72, v81
	v_fmac_f32_e32 v17, 0x3e38aa3b, v19
	v_cndmask_b32_e32 v16, v179, v16, vcc
	v_cmp_gt_u32_e32 vcc, s71, v18
	v_add_u32_e32 v19, 0x71, v81
	v_add_u32_e32 v83, 0x70, v81
	v_cndmask_b32_e32 v18, v179, v84, vcc
	v_cmp_gt_u32_e32 vcc, s71, v19
	v_exp_f32_e32 v84, v18
	s_nop 0
	v_cndmask_b32_e32 v19, v179, v85, vcc
	v_cmp_gt_u32_e32 vcc, s71, v83
	v_exp_f32_e32 v83, v16
	v_fma_f32 v16, -v146, v82, v189
	v_cndmask_b32_e32 v17, v179, v17, vcc
	v_exp_f32_e32 v109, v17
	v_fmamk_f32 v17, v20, 0x3e38aa3b, v16
	v_add_f32_e32 v18, v146, v16
	v_add_u32_e32 v20, 0x63, v81
	v_exp_f32_e32 v85, v19
	v_fmac_f32_e32 v18, 0x3e38aa3b, v21
	v_add_f32_e32 v19, v137, v16
	v_cmp_gt_u32_e32 vcc, s71, v20
	v_add_u32_e32 v20, 0x62, v81
	v_fmac_f32_e32 v19, 0x3e38aa3b, v22
	v_add_f32_e32 v16, v188, v16
	v_cndmask_b32_e32 v17, v179, v17, vcc
	v_cmp_gt_u32_e32 vcc, s71, v20
	v_add_u32_e32 v20, 0x61, v81
	v_fmac_f32_e32 v16, 0x3e38aa3b, v23
	v_cndmask_b32_e32 v18, v179, v18, vcc
	v_cmp_gt_u32_e32 vcc, s71, v20
	v_add_u32_e32 v20, 0x60, v81
	v_exp_f32_e32 v112, v17
	v_cndmask_b32_e32 v19, v179, v19, vcc
	v_cmp_gt_u32_e32 vcc, s71, v20
	v_exp_f32_e32 v113, v18
	v_add_u32_e32 v20, 0x53, v81
	v_cndmask_b32_e32 v16, v179, v16, vcc
	v_exp_f32_e32 v115, v16
	v_fma_f32 v16, -v146, v82, v190
	v_fmamk_f32 v17, v24, 0x3e38aa3b, v16
	v_add_f32_e32 v18, v146, v16
	v_exp_f32_e32 v114, v19
	v_fmac_f32_e32 v18, 0x3e38aa3b, v25
	v_add_f32_e32 v19, v137, v16
	v_cmp_gt_u32_e32 vcc, s71, v20
	v_add_u32_e32 v20, 0x52, v81
	v_fmac_f32_e32 v19, 0x3e38aa3b, v26
	v_add_f32_e32 v16, v188, v16
	v_cndmask_b32_e32 v17, v179, v17, vcc
	v_cmp_gt_u32_e32 vcc, s71, v20
	v_add_u32_e32 v20, 0x51, v81
	v_fmac_f32_e32 v16, 0x3e38aa3b, v27
	v_cndmask_b32_e32 v18, v179, v18, vcc
	v_cmp_gt_u32_e32 vcc, s71, v20
	v_add_u32_e32 v20, 0x50, v81
	v_exp_f32_e32 v116, v17
	v_cndmask_b32_e32 v19, v179, v19, vcc
	v_cmp_gt_u32_e32 vcc, s71, v20
	v_exp_f32_e32 v117, v18
	v_add_u32_e32 v20, 0x43, v81
	v_cndmask_b32_e32 v16, v179, v16, vcc
	v_exp_f32_e32 v139, v16
	v_fma_f32 v16, -v146, v82, v191
	v_fmamk_f32 v17, v28, 0x3e38aa3b, v16
	v_add_f32_e32 v18, v146, v16
	v_exp_f32_e32 v119, v19
	v_fmac_f32_e32 v18, 0x3e38aa3b, v29
	v_add_f32_e32 v19, v137, v16
	v_cmp_gt_u32_e32 vcc, s71, v20
	v_add_u32_e32 v20, 0x42, v81
	v_fmac_f32_e32 v19, 0x3e38aa3b, v30
	v_add_f32_e32 v16, v188, v16
	v_cndmask_b32_e32 v17, v179, v17, vcc
	v_cmp_gt_u32_e32 vcc, s71, v20
	v_add_u32_e32 v20, 0x41, v81
	v_fmac_f32_e32 v16, 0x3e38aa3b, v31
	v_cndmask_b32_e32 v18, v179, v18, vcc
	v_cmp_gt_u32_e32 vcc, s71, v20
	v_add_u32_e32 v20, 64, v81
	v_exp_f32_e32 v141, v17
	v_cndmask_b32_e32 v19, v179, v19, vcc
	v_cmp_gt_u32_e32 vcc, s71, v20
	v_exp_f32_e32 v143, v18
	v_exp_f32_e32 v147, v19
	v_cndmask_b32_e32 v16, v179, v16, vcc
	v_exp_f32_e32 v148, v16
	ds_read_b128 v[16:19], v118 offset:40960
	ds_read_b128 v[20:23], v118 offset:43520
	ds_read_b128 v[24:27], v118 offset:46080
	ds_read_b128 v[28:31], v118 offset:48640
	s_nop 0
	v_cvt_pk_bf16_f32 v110, v83, v84
	v_cvt_pk_bf16_f32 v111, v85, v109
	v_cvt_pk_bf16_f32 v112, v112, v113
	v_cvt_pk_bf16_f32 v113, v114, v115
	s_mov_b32 s30, s28
	s_mov_b32 s31, s28
	s_mov_b32 s29, s28
	v_mov_b64_e32 v[84:85], s[30:31]
	v_mov_b64_e32 v[82:83], s[28:29]
	s_waitcnt lgkmcnt(3)
	v_mfma_f32_16x16x32_bf16 v[16:19], v[16:19], v[110:113], v[90:93]
	s_waitcnt lgkmcnt(2)
	v_mfma_f32_16x16x32_bf16 v[20:23], v[20:23], v[110:113], v[94:97]
	s_waitcnt lgkmcnt(1)
	v_mfma_f32_16x16x32_bf16 v[24:27], v[24:27], v[110:113], v[98:101]
	s_waitcnt lgkmcnt(0)
	v_mfma_f32_16x16x32_bf16 v[28:31], v[28:31], v[110:113], v[102:105]
	v_mfma_f32_16x16x32_bf16 v[86:89], v[82:85], v[110:113], v[86:89]
	ds_read_b128 v[90:93], v118 offset:41024
	ds_read_b128 v[94:97], v118 offset:43584
	ds_read_b128 v[98:101], v118 offset:46144
	ds_read_b128 v[102:105], v118 offset:48704
	v_cvt_pk_bf16_f32 v110, v116, v117
	v_cvt_pk_bf16_f32 v111, v119, v139
	v_cvt_pk_bf16_f32 v112, v141, v143
	v_cvt_pk_bf16_f32 v113, v147, v148
	s_waitcnt lgkmcnt(3)
	v_mfma_f32_16x16x32_bf16 v[16:19], v[90:93], v[110:113], v[16:19]
	s_waitcnt lgkmcnt(2)
	v_mfma_f32_16x16x32_bf16 v[20:23], v[94:97], v[110:113], v[20:23]
	s_waitcnt lgkmcnt(1)
	v_mfma_f32_16x16x32_bf16 v[24:27], v[98:101], v[110:113], v[24:27]
	s_waitcnt lgkmcnt(0)
	v_mfma_f32_16x16x32_bf16 v[28:31], v[102:105], v[110:113], v[28:31]
	v_mfma_f32_16x16x32_bf16 v[86:89], v[82:85], v[110:113], v[86:89]
	s_and_b32 s0, s25, 0xc0
	s_mulk_i32 s0, 0xa0
	v_add_u32_e32 v118, s0, v153
	ds_read_b128 v[90:93], v118
	ds_read_b128 v[94:97], v118 offset:64
	ds_read_b128 v[98:101], v118 offset:2560
	ds_read_b128 v[102:105], v118 offset:2624
	ds_read_b128 v[110:113], v118 offset:5120
	ds_read_b128 v[114:117], v118 offset:5184
	ds_read_b128 v[194:197], v118 offset:7680
	ds_read_b128 v[198:201], v118 offset:7744
	s_waitcnt lgkmcnt(7)
	v_mfma_f32_16x16x32_bf16 v[90:93], v[90:93], v[60:63], 0
	s_waitcnt lgkmcnt(6)
	v_mfma_f32_16x16x32_bf16 v[90:93], v[94:97], v[56:59], v[90:93]
	s_waitcnt lgkmcnt(5)
	v_mfma_f32_16x16x32_bf16 v[94:97], v[98:101], v[60:63], 0
	s_waitcnt lgkmcnt(4)
	v_mfma_f32_16x16x32_bf16 v[94:97], v[102:105], v[56:59], v[94:97]
	s_waitcnt lgkmcnt(3)
	v_mfma_f32_16x16x32_bf16 v[98:101], v[110:113], v[60:63], 0
	s_waitcnt lgkmcnt(1)
	v_mfma_f32_16x16x32_bf16 v[102:105], v[194:197], v[60:63], 0
	v_mfma_f32_16x16x32_bf16 v[98:101], v[114:117], v[56:59], v[98:101]
	s_waitcnt lgkmcnt(0)
	v_mfma_f32_16x16x32_bf16 v[102:105], v[198:201], v[56:59], v[102:105]
	v_cvt_f32_i32_e32 v109, v108
	v_cmp_gt_u32_e32 vcc, s71, v108
	v_add_u32_e32 v108, 48, v81
	v_fma_f32 v110, -v146, v109, v192
	v_fmamk_f32 v90, v90, 0x3e38aa3b, v110
	v_add_f32_e32 v111, v146, v110
	v_add_f32_e32 v112, v137, v110
	v_fmac_f32_e32 v111, 0x3e38aa3b, v91
	v_fmac_f32_e32 v112, 0x3e38aa3b, v92
	v_add_f32_e32 v91, v188, v110
	v_add_u32_e32 v92, 50, v81
	v_fmac_f32_e32 v91, 0x3e38aa3b, v93
	v_cndmask_b32_e32 v90, v179, v90, vcc
	v_cmp_gt_u32_e32 vcc, s71, v92
	v_add_u32_e32 v93, 49, v81
	s_nop 0
	v_cndmask_b32_e32 v92, v179, v111, vcc
	v_cmp_gt_u32_e32 vcc, s71, v93
	v_exp_f32_e32 v110, v92
	s_nop 0
	v_cndmask_b32_e32 v93, v179, v112, vcc
	v_cmp_gt_u32_e32 vcc, s71, v108
	v_exp_f32_e32 v108, v90
	v_fma_f32 v90, -v146, v109, v189
	v_cndmask_b32_e32 v91, v179, v91, vcc
	v_exp_f32_e32 v112, v91
	v_fmamk_f32 v91, v94, 0x3e38aa3b, v90
	v_add_f32_e32 v92, v146, v90
	v_add_u32_e32 v94, 35, v81
	v_exp_f32_e32 v111, v93
	v_fmac_f32_e32 v92, 0x3e38aa3b, v95
	v_add_f32_e32 v93, v137, v90
	v_cmp_gt_u32_e32 vcc, s71, v94
	v_add_u32_e32 v94, 34, v81
	v_fmac_f32_e32 v93, 0x3e38aa3b, v96
	v_add_f32_e32 v90, v188, v90
	v_cndmask_b32_e32 v91, v179, v91, vcc
	v_cmp_gt_u32_e32 vcc, s71, v94
	v_add_u32_e32 v94, 33, v81
	v_fmac_f32_e32 v90, 0x3e38aa3b, v97
	v_cndmask_b32_e32 v92, v179, v92, vcc
	v_cmp_gt_u32_e32 vcc, s71, v94
	v_add_u32_e32 v94, 32, v81
	v_exp_f32_e32 v113, v91
	v_cndmask_b32_e32 v93, v179, v93, vcc
	v_cmp_gt_u32_e32 vcc, s71, v94
	v_exp_f32_e32 v114, v92
	v_add_u32_e32 v94, 19, v81
	v_cndmask_b32_e32 v90, v179, v90, vcc
	v_exp_f32_e32 v116, v90
	v_fma_f32 v90, -v146, v109, v190
	v_fmamk_f32 v91, v98, 0x3e38aa3b, v90
	v_add_f32_e32 v92, v146, v90
	v_exp_f32_e32 v115, v93
	v_fmac_f32_e32 v92, 0x3e38aa3b, v99
	v_add_f32_e32 v93, v137, v90
	v_cmp_gt_u32_e32 vcc, s71, v94
	v_add_u32_e32 v94, 18, v81
	v_fmac_f32_e32 v93, 0x3e38aa3b, v100
	v_add_f32_e32 v90, v188, v90
	v_cndmask_b32_e32 v91, v179, v91, vcc
	v_cmp_gt_u32_e32 vcc, s71, v94
	v_add_u32_e32 v94, 17, v81
	v_fmac_f32_e32 v90, 0x3e38aa3b, v101
	v_cndmask_b32_e32 v92, v179, v92, vcc
	v_cmp_gt_u32_e32 vcc, s71, v94
	v_add_u32_e32 v94, 16, v81
	v_exp_f32_e32 v117, v91
	v_cndmask_b32_e32 v93, v179, v93, vcc
	v_cmp_gt_u32_e32 vcc, s71, v94
	v_exp_f32_e32 v119, v92
	v_add_u32_e32 v94, 3, v81
	v_cndmask_b32_e32 v90, v179, v90, vcc
	v_exp_f32_e32 v141, v90
	v_fma_f32 v90, -v146, v109, v191
	v_fmamk_f32 v91, v102, 0x3e38aa3b, v90
	v_add_f32_e32 v92, v146, v90
	v_exp_f32_e32 v139, v93
	v_fmac_f32_e32 v92, 0x3e38aa3b, v103
	v_add_f32_e32 v93, v137, v90
	v_cmp_gt_u32_e32 vcc, s71, v94
	v_add_u32_e32 v94, 2, v81
	v_fmac_f32_e32 v93, 0x3e38aa3b, v104
	v_add_f32_e32 v90, v188, v90
	v_cndmask_b32_e32 v91, v179, v91, vcc
	v_cmp_gt_u32_e32 vcc, s71, v94
	v_add_u32_e32 v94, 1, v81
	v_fmac_f32_e32 v90, 0x3e38aa3b, v105
	v_cndmask_b32_e32 v92, v179, v92, vcc
	v_cmp_gt_u32_e32 vcc, s71, v94
	v_exp_f32_e32 v143, v91
	v_exp_f32_e32 v147, v92
	v_cndmask_b32_e32 v93, v179, v93, vcc
	v_cmp_gt_u32_e32 vcc, s71, v81
	v_exp_f32_e32 v148, v93
	s_nop 0
	v_cndmask_b32_e32 v90, v179, v90, vcc
	v_exp_f32_e32 v149, v90
	ds_read_b128 v[90:93], v118 offset:40960
	ds_read_b128 v[94:97], v118 offset:43520
	ds_read_b128 v[98:101], v118 offset:46080
	ds_read_b128 v[102:105], v118 offset:48640
	v_cvt_pk_bf16_f32 v108, v108, v110
	v_cvt_pk_bf16_f32 v109, v111, v112
	v_cvt_pk_bf16_f32 v110, v113, v114
	v_cvt_pk_bf16_f32 v111, v115, v116
	s_waitcnt lgkmcnt(3)
	v_mfma_f32_16x16x32_bf16 v[16:19], v[90:93], v[108:111], v[16:19]
	s_waitcnt lgkmcnt(2)
	v_mfma_f32_16x16x32_bf16 v[20:23], v[94:97], v[108:111], v[20:23]
	s_waitcnt lgkmcnt(1)
	v_mfma_f32_16x16x32_bf16 v[24:27], v[98:101], v[108:111], v[24:27]
	s_waitcnt lgkmcnt(0)
	v_mfma_f32_16x16x32_bf16 v[28:31], v[102:105], v[108:111], v[28:31]
	v_mfma_f32_16x16x32_bf16 v[86:89], v[82:85], v[108:111], v[86:89]
	ds_read_b128 v[90:93], v118 offset:41024
	ds_read_b128 v[94:97], v118 offset:43584
	ds_read_b128 v[98:101], v118 offset:46144
	ds_read_b128 v[102:105], v118 offset:48704
	v_cvt_pk_bf16_f32 v108, v117, v119
	v_cvt_pk_bf16_f32 v109, v139, v141
	v_cvt_pk_bf16_f32 v110, v143, v147
	v_cvt_pk_bf16_f32 v111, v148, v149
	s_waitcnt lgkmcnt(3)
	v_mfma_f32_16x16x32_bf16 v[16:19], v[90:93], v[108:111], v[16:19]
	s_waitcnt lgkmcnt(2)
	v_mfma_f32_16x16x32_bf16 v[20:23], v[94:97], v[108:111], v[20:23]
	s_waitcnt lgkmcnt(1)
	v_mfma_f32_16x16x32_bf16 v[24:27], v[98:101], v[108:111], v[24:27]
	s_waitcnt lgkmcnt(0)
	v_mfma_f32_16x16x32_bf16 v[28:31], v[102:105], v[108:111], v[28:31]
	v_mfma_f32_16x16x32_bf16 v[82:85], v[82:85], v[108:111], v[86:89]
.LBB0_1066:
	s_add_i32 s0, s24, 0x80
	s_and_b32 s1, s0, 0x80
	s_mulk_i32 s1, 0xa0
	v_add_u32_e32 v86, s1, v151
	s_waitcnt vmcnt(3)
	ds_write_b128 v86, v[36:39]
	v_add_u32_e32 v36, s1, v152
	s_add_i32 s1, s24, 0xc0
	s_and_b32 s1, s1, 0xc0
	v_add_u32_e32 v36, 0xa000, v36
	s_mulk_i32 s1, 0xa0
	s_waitcnt vmcnt(2)
	ds_write2_b64 v36, v[32:33], v[34:35] offset1:2
	v_add_u32_e32 v32, s1, v151
	s_waitcnt vmcnt(1)
	ds_write_b128 v32, v[44:47]
	v_add_u32_e32 v32, s1, v152
	s_add_i32 s1, s23, -1
	s_min_i32 s1, s1, s21
	s_lshl_b32 s1, s1, 6
	s_add_i32 s24, s1, s20
	s_min_i32 s1, s23, s21
	s_ashr_i32 s25, s24, 31
	s_lshl_b32 s1, s1, 6
	s_lshl_b64 s[26:27], s[24:25], 12
	v_lshl_add_u64 v[34:35], s[24:25], 1, v[106:107]
	s_add_i32 s24, s1, s20
	v_add_u32_e32 v32, 0xa000, v32
	s_ashr_i32 s25, s24, 31
	s_waitcnt vmcnt(0)
	ds_write2_b64 v32, v[40:41], v[42:43] offset1:2
	s_add_i32 s98, s23, -1
	s_cmp_gt_i32 s98, s21
	s_cbranch_scc1 .Lwin_skip_pf
	v_lshl_add_u64 v[32:33], v[120:121], 0, s[26:27]
	s_lshl_b64 s[26:27], s[24:25], 12
	global_load_dwordx4 v[36:39], v[32:33], off offset:3072
	s_nop 0
	global_load_dwordx4 v[32:35], v[34:35], off
	v_lshl_add_u64 v[40:41], v[120:121], 0, s[26:27]
	v_lshl_add_u64 v[42:43], s[24:25], 1, v[106:107]
	global_load_dwordx4 v[44:47], v[40:41], off offset:3072
	s_nop 0
	global_load_dwordx4 v[40:43], v[42:43], off

.LBB0_1069:
	s_cmp_gt_i32 s23, s21
	s_cbranch_scc1 .LBB0_986
	s_lshl_b32 s22, s23, 6
	s_add_i32 s23, s22, s20
	s_or_b32 s0, s23, 63
	s_cmp_gt_i32 s0, s74
	s_cselect_b64 s[0:1], -1, 0
	s_addk_i32 s74, 0xfe10
	s_cmp_lt_i32 s23, s74
	s_cselect_b64 s[20:21], -1, 0
	s_and_b32 s22, s22, 0x80
	s_mulk_i32 s22, 0xa0
	v_add_u32_e32 v81, s22, v153
	ds_read_b128 v[102:105], v81
	ds_read_b128 v[106:109], v81 offset:64
	ds_read_b128 v[110:113], v81 offset:2560
	ds_read_b128 v[114:117], v81 offset:2624
	ds_read_b128 v[86:89], v81 offset:5120
	ds_read_b128 v[90:93], v81 offset:5184
	ds_read_b128 v[94:97], v81 offset:7680
	ds_read_b128 v[98:101], v81 offset:7744
	s_waitcnt vmcnt(2)
	v_or_b32_e32 v32, s23, v124
	v_sub_u32_e32 v137, v144, v32
	s_or_b64 s[20:21], s[0:1], s[20:21]
	v_cvt_f32_i32_e32 v143, v137
	s_mov_b64 s[0:1], -1
	s_and_b64 vcc, exec, s[20:21]
	s_cbranch_vccnz .LBB0_1072
	s_waitcnt lgkmcnt(7)
	v_mfma_f32_16x16x32_bf16 v[32:35], v[102:105], v[60:63], 0
	s_waitcnt lgkmcnt(5)
	v_mfma_f32_16x16x32_bf16 v[36:39], v[110:113], v[60:63], 0
	s_waitcnt vmcnt(0) lgkmcnt(3)
	v_mfma_f32_16x16x32_bf16 v[40:43], v[86:89], v[60:63], 0
	s_waitcnt lgkmcnt(1)
	v_mfma_f32_16x16x32_bf16 v[44:47], v[94:97], v[60:63], 0
	v_mfma_f32_16x16x32_bf16 v[32:35], v[106:109], v[56:59], v[32:35]
	v_mfma_f32_16x16x32_bf16 v[36:39], v[114:117], v[56:59], v[36:39]
	v_mfma_f32_16x16x32_bf16 v[40:43], v[90:93], v[56:59], v[40:43]
	s_waitcnt lgkmcnt(0)
	v_mfma_f32_16x16x32_bf16 v[44:47], v[98:101], v[56:59], v[44:47]
	v_pk_mul_f32 v[118:119], v[146:147], v[142:143] op_sel_hi:[0,1] neg_hi:[1,0]
	v_fma_f32 v120, 0, v146, v119
	s_nop 0
	v_fmamk_f32 v32, v32, 0x3e38aa3b, v120
	v_add_f32_e32 v121, v146, v120
	v_mov_b32_e32 v147, v38
	v_fmac_f32_e32 v121, 0x3e38aa3b, v33
	v_exp_f32_e32 v139, v32
	v_add_f32_e32 v118, v118, v119
	v_pk_mul_f32 v[32:33], v[146:147], s[44:45]
	v_fmamk_f32 v141, v36, 0x3e38aa3b, v118
	v_add_f32_e32 v36, v32, v120
	v_fmac_f32_e32 v36, 0x3e38aa3b, v34
	v_add_f32_e32 v148, v146, v118
	v_mov_b32_e32 v147, v39
	s_mov_b32 s47, s45
	v_fmac_f32_e32 v148, 0x3e38aa3b, v37
	v_exp_f32_e32 v149, v36
	v_add_f32_e32 v34, v32, v118
	v_pk_mul_f32 v[36:37], v[146:147], s[46:47]
	v_add_f32_e32 v33, v34, v33
	v_add_f32_e32 v34, v36, v120
	v_fmac_f32_e32 v34, 0x3e38aa3b, v35
	s_nop 0
	v_exp_f32_e32 v120, v34
	v_add_f32_e32 v34, v36, v118
	v_add_f32_e32 v34, v34, v37
	v_exp_f32_e32 v147, v148
	v_exp_f32_e32 v148, v33
	v_fmamk_f32 v33, v146, 0x42000000, v119
	v_add_f32_e32 v35, v146, v33
	v_exp_f32_e32 v186, v34
	v_fmamk_f32 v34, v40, 0x3e38aa3b, v33
	v_fmac_f32_e32 v35, 0x3e38aa3b, v41
	v_add_f32_e32 v37, v32, v33
	v_add_f32_e32 v33, v36, v33
	v_fmac_f32_e32 v33, 0x3e38aa3b, v43
	v_fmac_f32_e32 v119, 0x42400000, v146
	v_exp_f32_e32 v206, v34
	v_exp_f32_e32 v207, v35
	v_add_f32_e32 v34, v146, v119
	v_add_f32_e32 v32, v32, v119
	v_add_f32_e32 v35, v36, v119
	v_fmac_f32_e32 v37, 0x3e38aa3b, v42
	v_exp_f32_e32 v209, v33
	v_fmamk_f32 v33, v44, 0x3e38aa3b, v119
	v_fmac_f32_e32 v34, 0x3e38aa3b, v45
	v_fmac_f32_e32 v32, 0x3e38aa3b, v46
	v_fmac_f32_e32 v35, 0x3e38aa3b, v47
	v_exp_f32_e32 v121, v121
	v_exp_f32_e32 v208, v37
	v_exp_f32_e32 v210, v33
	v_exp_f32_e32 v211, v34
	v_exp_f32_e32 v212, v32
	v_exp_f32_e32 v213, v35
	ds_read_b128 v[32:35], v81 offset:40960
	ds_read_b128 v[36:39], v81 offset:43520
	ds_read_b128 v[40:43], v81 offset:46080
	ds_read_b128 v[44:47], v81 offset:48640
	v_exp_f32_e32 v141, v141
	v_cvt_pk_bf16_f32 v118, v139, v121
	v_cvt_pk_bf16_f32 v119, v149, v120
	v_cvt_pk_bf16_f32 v120, v141, v147
	v_cvt_pk_bf16_f32 v121, v148, v186
	s_mov_b32 s30, s28
	s_mov_b32 s31, s28
	s_mov_b32 s29, s28
	v_mov_b64_e32 v[188:189], s[30:31]
	v_mov_b64_e32 v[186:187], s[28:29]
	s_waitcnt lgkmcnt(3)
	v_mfma_f32_16x16x32_bf16 v[32:35], v[32:35], v[118:121], v[16:19]
	s_waitcnt lgkmcnt(2)
	v_mfma_f32_16x16x32_bf16 v[36:39], v[36:39], v[118:121], v[20:23]
	s_waitcnt lgkmcnt(1)
	v_mfma_f32_16x16x32_bf16 v[40:43], v[40:43], v[118:121], v[24:27]
	s_waitcnt lgkmcnt(0)
	v_mfma_f32_16x16x32_bf16 v[44:47], v[44:47], v[118:121], v[28:31]
	v_mfma_f32_16x16x32_bf16 v[118:121], v[186:189], v[118:121], v[82:85]
	ds_read_b128 v[190:193], v81 offset:41024
	ds_read_b128 v[194:197], v81 offset:43584
	ds_read_b128 v[198:201], v81 offset:46144
	ds_read_b128 v[202:205], v81 offset:48704
	v_cvt_pk_bf16_f32 v206, v206, v207
	v_cvt_pk_bf16_f32 v207, v208, v209
	v_cvt_pk_bf16_f32 v208, v210, v211
	v_cvt_pk_bf16_f32 v209, v212, v213
	s_waitcnt lgkmcnt(3)
	v_mfma_f32_16x16x32_bf16 v[32:35], v[190:193], v[206:209], v[32:35]
	s_mov_b64 s[0:1], 0
	s_waitcnt lgkmcnt(2)
	v_mfma_f32_16x16x32_bf16 v[36:39], v[194:197], v[206:209], v[36:39]
	s_waitcnt lgkmcnt(1)
	v_mfma_f32_16x16x32_bf16 v[40:43], v[198:201], v[206:209], v[40:43]
	s_waitcnt lgkmcnt(0)
	v_mfma_f32_16x16x32_bf16 v[44:47], v[202:205], v[206:209], v[44:47]
	v_mfma_f32_16x16x32_bf16 v[118:121], v[186:189], v[206:209], v[118:121]
.LBB0_1072:
	s_andn2_b64 vcc, exec, s[0:1]
	s_cbranch_vccnz .LBB0_985
	s_waitcnt lgkmcnt(7)
	v_mfma_f32_16x16x32_bf16 v[32:35], v[102:105], v[60:63], 0
	s_waitcnt lgkmcnt(5)
	v_mfma_f32_16x16x32_bf16 v[36:39], v[110:113], v[60:63], 0
	s_waitcnt vmcnt(0) lgkmcnt(3)
	v_mfma_f32_16x16x32_bf16 v[40:43], v[86:89], v[60:63], 0
	s_waitcnt lgkmcnt(1)
	v_mfma_f32_16x16x32_bf16 v[44:47], v[94:97], v[60:63], 0
	v_mfma_f32_16x16x32_bf16 v[32:35], v[106:109], v[56:59], v[32:35]
	v_mfma_f32_16x16x32_bf16 v[36:39], v[114:117], v[56:59], v[36:39]
	v_mfma_f32_16x16x32_bf16 v[40:43], v[90:93], v[56:59], v[40:43]
	s_waitcnt lgkmcnt(0)
	v_mfma_f32_16x16x32_bf16 v[44:47], v[98:101], v[56:59], v[44:47]
	v_pk_mul_f32 v[56:57], v[146:147], v[142:143] op_sel_hi:[0,1]
	v_fma_f32 v61, v146, 0, -v57
	s_nop 0
	v_fmamk_f32 v32, v32, 0x3e38aa3b, v61
	v_add_u32_e32 v58, -1, v137
	v_add_f32_e32 v62, v146, v61
	v_cmp_gt_u32_e32 vcc, s71, v137
	v_fmac_f32_e32 v62, 0x3e38aa3b, v33
	v_mov_b32_e32 v147, v38
	v_cndmask_b32_e32 v32, v179, v32, vcc
	v_cmp_gt_u32_e32 vcc, s71, v58
	v_exp_f32_e32 v58, v32
	v_sub_f32_e32 v56, v56, v57
	v_cndmask_b32_e32 v33, v179, v62, vcc
	v_exp_f32_e32 v62, v33
	v_pk_mul_f32 v[32:33], v[146:147], s[44:45]
	v_add_u32_e32 v59, -2, v137
	v_fmamk_f32 v63, v36, 0x3e38aa3b, v56
	v_add_f32_e32 v36, v32, v61
	v_fmac_f32_e32 v36, 0x3e38aa3b, v34
	v_cmp_gt_u32_e32 vcc, s71, v59
	v_add_f32_e32 v86, v146, v56
	v_mov_b32_e32 v147, v39
	v_cndmask_b32_e32 v34, v179, v36, vcc
	s_mov_b32 s47, s45
	v_fmac_f32_e32 v86, 0x3e38aa3b, v37
	v_exp_f32_e32 v59, v34
	v_add_f32_e32 v34, v32, v56
	v_pk_mul_f32 v[36:37], v[146:147], s[46:47]
	v_add_f32_e32 v33, v34, v33
	v_add_f32_e32 v34, v36, v61
	v_add_u32_e32 v60, -3, v137
	v_fmac_f32_e32 v34, 0x3e38aa3b, v35
	v_cmp_gt_u32_e32 vcc, s71, v60
	v_add_u32_e32 v35, -16, v137
	v_subrev_u32_e32 v38, 18, v137
	v_cndmask_b32_e32 v34, v179, v34, vcc
	v_exp_f32_e32 v60, v34
	v_add_f32_e32 v34, v36, v56
	v_add_f32_e32 v34, v34, v37
	v_cmp_gt_u32_e32 vcc, s71, v35
	v_subrev_u32_e32 v37, 17, v137
	s_nop 0
	v_cndmask_b32_e32 v35, v179, v63, vcc
	v_cmp_gt_u32_e32 vcc, s71, v37
	v_exp_f32_e32 v61, v35
	s_nop 0
	v_cndmask_b32_e32 v37, v179, v86, vcc
	v_cmp_gt_u32_e32 vcc, s71, v38
	v_subrev_u32_e32 v38, 19, v137
	v_exp_f32_e32 v63, v37
	v_cndmask_b32_e32 v33, v179, v33, vcc
	v_cmp_gt_u32_e32 vcc, s71, v38
	v_exp_f32_e32 v86, v33
	v_fma_f32 v33, v146, s65, -v57
	v_cndmask_b32_e32 v34, v179, v34, vcc
	v_exp_f32_e32 v87, v34
	v_fmamk_f32 v34, v40, 0x3e38aa3b, v33
	v_add_f32_e32 v35, v146, v33
	v_subrev_u32_e32 v38, 32, v137
	v_fmac_f32_e32 v35, 0x3e38aa3b, v41
	v_add_f32_e32 v37, v32, v33
	v_cmp_gt_u32_e32 vcc, s71, v38
	v_subrev_u32_e32 v38, 33, v137
	v_fmac_f32_e32 v37, 0x3e38aa3b, v42
	v_add_f32_e32 v33, v36, v33
	v_cndmask_b32_e32 v34, v179, v34, vcc
	v_cmp_gt_u32_e32 vcc, s71, v38
	v_subrev_u32_e32 v38, 34, v137
	v_fmac_f32_e32 v33, 0x3e38aa3b, v43
	v_cndmask_b32_e32 v35, v179, v35, vcc
	v_cmp_gt_u32_e32 vcc, s71, v38
	v_subrev_u32_e32 v38, 35, v137
	v_exp_f32_e32 v88, v34
	v_cndmask_b32_e32 v37, v179, v37, vcc
	v_cmp_gt_u32_e32 vcc, s71, v38
	v_exp_f32_e32 v89, v35
	v_exp_f32_e32 v90, v37
	v_cndmask_b32_e32 v33, v179, v33, vcc
	v_exp_f32_e32 v91, v33
	v_fma_f32 v33, v146, s66, -v57
	v_fmamk_f32 v34, v44, 0x3e38aa3b, v33
	v_add_f32_e32 v35, v146, v33
	v_add_f32_e32 v32, v32, v33
	v_add_f32_e32 v33, v36, v33
	v_subrev_u32_e32 v36, 48, v137
	v_fmac_f32_e32 v35, 0x3e38aa3b, v45
	v_cmp_gt_u32_e32 vcc, s71, v36
	v_subrev_u32_e32 v36, 49, v137
	v_fmac_f32_e32 v32, 0x3e38aa3b, v46
	v_cndmask_b32_e32 v34, v179, v34, vcc
	v_cmp_gt_u32_e32 vcc, s71, v36
	v_subrev_u32_e32 v36, 50, v137
	v_fmac_f32_e32 v33, 0x3e38aa3b, v47
	v_cndmask_b32_e32 v35, v179, v35, vcc
	v_cmp_gt_u32_e32 vcc, s71, v36
	v_subrev_u32_e32 v36, 51, v137
	v_exp_f32_e32 v92, v34
	v_cndmask_b32_e32 v32, v179, v32, vcc
	v_cmp_gt_u32_e32 vcc, s71, v36
	v_exp_f32_e32 v93, v35
	v_exp_f32_e32 v94, v32
	v_cndmask_b32_e32 v33, v179, v33, vcc
	v_exp_f32_e32 v95, v33
	ds_read_b128 v[32:35], v81 offset:40960
	ds_read_b128 v[36:39], v81 offset:43520
	ds_read_b128 v[40:43], v81 offset:46080
	ds_read_b128 v[44:47], v81 offset:48640
	v_cvt_pk_bf16_f32 v56, v58, v62
	v_cvt_pk_bf16_f32 v57, v59, v60
	v_cvt_pk_bf16_f32 v58, v61, v63
	v_cvt_pk_bf16_f32 v59, v86, v87
	s_mov_b32 s30, s28
	s_mov_b32 s31, s28
	s_mov_b32 s29, s28
	v_mov_b64_e32 v[62:63], s[30:31]
	v_mov_b64_e32 v[60:61], s[28:29]
	s_waitcnt lgkmcnt(3)
	v_mfma_f32_16x16x32_bf16 v[16:19], v[32:35], v[56:59], v[16:19]
	s_waitcnt lgkmcnt(2)
	v_mfma_f32_16x16x32_bf16 v[20:23], v[36:39], v[56:59], v[20:23]
	s_waitcnt lgkmcnt(1)
	v_mfma_f32_16x16x32_bf16 v[24:27], v[40:43], v[56:59], v[24:27]
	s_waitcnt lgkmcnt(0)
	v_mfma_f32_16x16x32_bf16 v[28:31], v[44:47], v[56:59], v[28:31]
	v_mfma_f32_16x16x32_bf16 v[56:59], v[60:63], v[56:59], v[82:85]
	ds_read_b128 v[32:35], v81 offset:41024
	ds_read_b128 v[36:39], v81 offset:43584
	ds_read_b128 v[40:43], v81 offset:46144
	ds_read_b128 v[44:47], v81 offset:48704
	v_cvt_pk_bf16_f32 v82, v88, v89
	v_cvt_pk_bf16_f32 v83, v90, v91
	v_cvt_pk_bf16_f32 v84, v92, v93
	v_cvt_pk_bf16_f32 v85, v94, v95
	s_waitcnt lgkmcnt(3)
	v_mfma_f32_16x16x32_bf16 v[32:35], v[32:35], v[82:85], v[16:19]
	s_waitcnt lgkmcnt(2)
	v_mfma_f32_16x16x32_bf16 v[36:39], v[36:39], v[82:85], v[20:23]
	s_waitcnt lgkmcnt(1)
	v_mfma_f32_16x16x32_bf16 v[40:43], v[40:43], v[82:85], v[24:27]
	s_waitcnt lgkmcnt(0)
	v_mfma_f32_16x16x32_bf16 v[44:47], v[44:47], v[82:85], v[28:31]
	v_mfma_f32_16x16x32_bf16 v[118:121], v[60:63], v[82:85], v[56:59]
	s_branch .LBB0_985
